# GEMM priority flips inverted: raised while a wave issues ds_read / LDS-DMA, lowered during its MFMA burst
# speedup vs baseline: 1.0057x; 1.0043x over previous
; #define PG8_STAGE(bufoff, gbase, voff) do { _Pragma("unroll") for (int _i = 0; _i < 2; ++_i) \
;         __builtin_amdgcn_global_load_lds((const unsigned*)((const char*)(gbase) + (voff)[_i]), (LAS unsigned*)(lds + (bufoff) + ldsw + _i * 8192), 16, 0, 0); } while (0)
; #define PG8_LDA(dst, b, h) do { _Pragma("unroll") for (int m = 0; m < 4; ++m) _Pragma("unroll") for (int k = 0; k < 2; ++k) dst[m][k] = *(const LAS bf16x8*)(lds + PG8_SA(b, h) + aoff + m * 2048 + k * 1024); } while (0)
; #define PG8_LDB(dst, b, h) do { _Pragma("unroll") for (int n = 0; n < 2; ++n) _Pragma("unroll") for (int k = 0; k < 2; ++k) dst[n][k] = *(const LAS bf16x8*)(lds + PG8_SB(b, h) + boff + n * 2048 + k * 1024); } while (0)
; #define PG8_MMA(ai, bj, At, Bt_) do { __builtin_amdgcn_s_setprio(1); _Pragma("unroll") for (int m = 0; m < 4; ++m) _Pragma("unroll") for (int n = 0; n < 2; ++n) _Pragma("unroll") for (int k = 0; k < 2; ++k) \
;         acc[ai][bj][m][n] = __builtin_amdgcn_mfma_f32_16x16x32_bf16(Bt_[n][k], At[m][k], acc[ai][bj][m][n], 0, 0, 0); __builtin_amdgcn_s_setprio(0); } while (0)
; #define PG8_WAIT_L(n) asm volatile("s_waitcnt lgkmcnt(" #n ")" ::: "memory")
; #define PG8_BAR __builtin_amdgcn_s_barrier()
; template <bool REMAP>
; DI void gemm_phase(LAS unsigned char* lds, const u16* A, int lda, const u16* Bt, int K, u16* O, int ldc, int nunits) {
;     ...
;         const bool has_next = next_unit(ui + 1, nunits, nxt);
;         const char* nA = has_next ? (const char*)A + (size_t)nxt.pm * tstepA : cA; const char* nB = has_next ? (const char*)Bt + (size_t)nxt.pn * tstepB : cB;
;         for (int t = 0; t < nt; t += 2) {
;             const bool last = (t == nt - 2);
;             const char* a1 = cA + akb(t + 1);
;             const char* a2 = last ? nA + akb(0) : cA + akb(t + 2); const char* b2 = last ? nB : cB + (size_t)(t + 2) * kstep;
;             const char* a3 = last ? nA + akb(1) : cA + akb(t + 3); const char* b3 = b2 + kstep;
;             PG8_LDB(B0, 0, 0); PG8_SCHED; PG8_LDA(At, 0, 0); PG8_STAGE(PG8_SA(1, 1), a1 + hstepA, voffA);
;             PG8_WAIT_L(8); PG8_BAR; PG8_WAIT_L(0); PG8_MMA(0, 0, At, B0); PG8_BAR; PG8_SCHED;
;             PG8_LDB(B1, 0, 1); PG8_STAGE(PG8_SB(0, 0), b2, voffB);
;             PG8_BAR; PG8_WAIT_L(0); PG8_MMA(0, 1, At, B1); PG8_BAR;
;             PG8_LDA(At, 0, 1); PG8_STAGE(PG8_SA(0, 0), a2, voffA);
.LBB0_136:
	s_ashr_i32 s5, s4, 31
	s_lshl_b64 s[12:13], s[4:5], 19
	s_add_u32 s12, s3, s12
	s_addc_u32 s13, s24, s13
	s_and_b64 s[14:15], s[22:23], exec
	s_cselect_b32 s5, s13, s11
	s_cselect_b32 s46, s12, s10
	s_ashr_i32 s7, s6, 31
	s_lshl_b64 s[14:15], s[6:7], 19
	s_add_u32 s14, s16, s14
	s_addc_u32 s15, s25, s15
	s_and_b64 s[22:23], s[22:23], exec
	s_cselect_b32 s7, s15, s21
	s_cselect_b32 s47, s14, s20
	s_add_u32 s49, s46, 0x80
	s_addc_u32 s50, s5, 0
	s_add_u32 s51, s20, 0x100
	s_addc_u32 s54, s21, 0
	s_add_u32 s22, s10, 0x40080
	s_addc_u32 s23, s11, 0
	s_mov_b32 s55, -2
	s_mov_b64 s[20:21], 0
	v_lshl_add_u64 v[140:141], s[22:23], 0, v[136:137]
	v_lshl_add_u64 v[142:143], s[22:23], 0, v[138:139]
	s_add_u32 s22, s10, s20
	s_addc_u32 s23, s11, s21
	s_add_u32 s30, s22, 0x100
	s_addc_u32 s31, s23, 0
	s_add_u32 s56, s51, s20
	s_addc_u32 s57, s54, s21
	s_add_u32 s22, s22, 0x180
	s_addc_u32 s23, s23, 0
	s_add_i32 s58, 0, 0x10000
	v_add_u32_e32 v160, s58, v145
	ds_read_b128 v[148:151], v160
	ds_read_b128 v[152:155], v160 offset:1024
	ds_read_b128 v[156:159], v160 offset:2048
	ds_read_b128 v[160:163], v160 offset:3072
	s_cmpk_eq_i32 s20, 0x700
	s_cselect_b32 s29, s50, s23
	s_cselect_b32 s28, s49, s22
	s_cselect_b32 s23, s7, s57
	s_cselect_b32 s22, s47, s56
	s_cselect_b32 s31, s5, s31
	s_cselect_b32 s30, s46, s30
	v_lshl_add_u64 v[172:173], v[142:143], 0, s[20:21]
	s_add_i32 m0, s27, 0xc000
	ds_read_b128 v[164:167], v147
	ds_read_b128 v[168:171], v147 offset:1024
	ds_read_b128 v[192:195], v147 offset:2048
	ds_read_b128 v[196:199], v147 offset:3072
	ds_read_b128 v[200:203], v147 offset:4096
	ds_read_b128 v[204:207], v147 offset:5120
	ds_read_b128 v[208:211], v147 offset:6144
	ds_read_b128 v[212:215], v147 offset:7168
	global_load_lds_dwordx4 v[172:173], off
	v_lshl_add_u64 v[172:173], v[140:141], 0, s[20:21]
	s_add_i32 m0, s27, 0xe000
	s_nop 0
	global_load_lds_dwordx4 v[172:173], off
	s_waitcnt lgkmcnt(8)
	s_barrier
	s_waitcnt lgkmcnt(0)
	s_setprio 0
	s_waitcnt lgkmcnt(0)
	v_mfma_f32_16x16x32_bf16 v[126:129], v[148:151], v[164:167], 0
	v_mfma_f32_16x16x32_bf16 v[122:125], v[156:159], v[164:167], 0
	v_mfma_f32_16x16x32_bf16 v[118:121], v[148:151], v[192:195], 0
	v_mfma_f32_16x16x32_bf16 v[114:117], v[156:159], v[192:195], 0
	v_mfma_f32_16x16x32_bf16 v[102:105], v[148:151], v[200:203], 0
	v_mfma_f32_16x16x32_bf16 v[98:101], v[156:159], v[200:203], 0
	v_mfma_f32_16x16x32_bf16 v[86:89], v[148:151], v[208:211], 0
	v_mfma_f32_16x16x32_bf16 v[82:85], v[156:159], v[208:211], 0
	v_mfma_f32_16x16x32_bf16 v[126:129], v[152:155], v[168:171], v[126:129]
	v_mfma_f32_16x16x32_bf16 v[122:125], v[160:163], v[168:171], v[122:125]
	v_mfma_f32_16x16x32_bf16 v[118:121], v[152:155], v[196:199], v[118:121]
	v_mfma_f32_16x16x32_bf16 v[114:117], v[160:163], v[196:199], v[114:117]
	v_mfma_f32_16x16x32_bf16 v[102:105], v[152:155], v[204:207], v[102:105]
	v_mfma_f32_16x16x32_bf16 v[98:101], v[160:163], v[204:207], v[98:101]
	v_mfma_f32_16x16x32_bf16 v[86:89], v[152:155], v[212:215], v[86:89]
	v_mfma_f32_16x16x32_bf16 v[82:85], v[160:163], v[212:215], v[82:85]
	s_setprio 1
	s_barrier
	s_add_i32 s59, 0, 0x14000
	v_add_u32_e32 v172, s59, v145
	s_add_i32 s56, s58, s26
	ds_read_b128 v[216:219], v172
	ds_read_b128 v[220:223], v172 offset:1024
	ds_read_b128 v[224:227], v172 offset:2048
	ds_read_b128 v[228:231], v172 offset:3072
	v_lshl_add_u64 v[172:173], s[22:23], 0, v[0:1]
	s_mov_b32 m0, s56
	v_lshl_add_u64 v[232:233], s[22:23], 0, v[130:131]
	global_load_lds_dwordx4 v[172:173], off
	s_add_i32 m0, s56, 0x2000
	s_nop 0
	global_load_lds_dwordx4 v[232:233], off
	s_barrier
	s_waitcnt lgkmcnt(0)
	s_setprio 0
	s_waitcnt lgkmcnt(0)
	v_mfma_f32_16x16x32_bf16 v[110:113], v[216:219], v[164:167], 0
	v_mfma_f32_16x16x32_bf16 v[106:109], v[224:227], v[164:167], 0
	v_mfma_f32_16x16x32_bf16 v[94:97], v[216:219], v[192:195], 0
	v_mfma_f32_16x16x32_bf16 v[90:93], v[224:227], v[192:195], 0
	v_mfma_f32_16x16x32_bf16 v[78:81], v[216:219], v[200:203], 0
	v_mfma_f32_16x16x32_bf16 v[74:77], v[224:227], v[200:203], 0
	v_mfma_f32_16x16x32_bf16 v[70:73], v[216:219], v[208:211], 0
	v_mfma_f32_16x16x32_bf16 v[66:69], v[224:227], v[208:211], 0
	v_mfma_f32_16x16x32_bf16 v[110:113], v[220:223], v[168:171], v[110:113]
	v_mfma_f32_16x16x32_bf16 v[106:109], v[228:231], v[168:171], v[106:109]
	v_mfma_f32_16x16x32_bf16 v[94:97], v[220:223], v[196:199], v[94:97]
	v_mfma_f32_16x16x32_bf16 v[90:93], v[228:231], v[196:199], v[90:93]
	v_mfma_f32_16x16x32_bf16 v[78:81], v[220:223], v[204:207], v[78:81]
	v_mfma_f32_16x16x32_bf16 v[74:77], v[228:231], v[204:207], v[74:77]
	v_mfma_f32_16x16x32_bf16 v[70:73], v[220:223], v[212:215], v[70:73]
	v_mfma_f32_16x16x32_bf16 v[66:69], v[228:231], v[212:215], v[66:69]
	s_setprio 1
	s_mov_b32 m0, s27
	v_lshl_add_u64 v[234:235], s[30:31], 0, v[134:135]
	s_barrier
	ds_read_b128 v[164:167], v147 offset:16384
	ds_read_b128 v[168:171], v147 offset:17408
	ds_read_b128 v[192:195], v147 offset:18432
	ds_read_b128 v[196:199], v147 offset:19456
	ds_read_b128 v[200:203], v147 offset:20480
	ds_read_b128 v[204:207], v147 offset:21504
	ds_read_b128 v[208:211], v147 offset:22528
	ds_read_b128 v[212:215], v147 offset:23552
	global_load_lds_dwordx4 v[234:235], off
	v_lshl_add_u64 v[234:235], s[30:31], 0, v[132:133]
	s_mov_b32 m0, s34
	s_nop 0
	global_load_lds_dwordx4 v[234:235], off
	s_barrier
; #define PG8_STAGE(bufoff, gbase, voff) do { _Pragma("unroll") for (int _i = 0; _i < 2; ++_i) \
;         __builtin_amdgcn_global_load_lds((const unsigned*)((const char*)(gbase) + (voff)[_i]), (LAS unsigned*)(lds + (bufoff) + ldsw + _i * 8192), 16, 0, 0); } while (0)
; #define PG8_LDA(dst, b, h) do { _Pragma("unroll") for (int m = 0; m < 4; ++m) _Pragma("unroll") for (int k = 0; k < 2; ++k) dst[m][k] = *(const LAS bf16x8*)(lds + PG8_SA(b, h) + aoff + m * 2048 + k * 1024); } while (0)
; #define PG8_LDB(dst, b, h) do { _Pragma("unroll") for (int n = 0; n < 2; ++n) _Pragma("unroll") for (int k = 0; k < 2; ++k) dst[n][k] = *(const LAS bf16x8*)(lds + PG8_SB(b, h) + boff + n * 2048 + k * 1024); } while (0)
; #define PG8_MMA(ai, bj, At, Bt_) do { __builtin_amdgcn_s_setprio(1); _Pragma("unroll") for (int m = 0; m < 4; ++m) _Pragma("unroll") for (int n = 0; n < 2; ++n) _Pragma("unroll") for (int k = 0; k < 2; ++k) \
;         acc[ai][bj][m][n] = __builtin_amdgcn_mfma_f32_16x16x32_bf16(Bt_[n][k], At[m][k], acc[ai][bj][m][n], 0, 0, 0); __builtin_amdgcn_s_setprio(0); } while (0)
; #define PG8_WAIT_V(n) asm volatile("s_waitcnt vmcnt(" #n ")" ::: "memory")
; #define PG8_WAIT_L(n) asm volatile("s_waitcnt lgkmcnt(" #n ")" ::: "memory")
; #define PG8_BAR __builtin_amdgcn_s_barrier()
; #define PG8_SCHED __builtin_amdgcn_sched_barrier(0)
; template <bool REMAP>
; DI void gemm_phase(LAS unsigned char* lds, const u16* A, int lda, const u16* Bt, int K, u16* O, int ldc, int nunits) {
;     ...
;             PG8_BAR; PG8_WAIT_L(0); PG8_MMA(1, 0, At, B0); PG8_BAR; PG8_SCHED;
;             PG8_STAGE(PG8_SB(0, 1), b2 + hstepB, voffB);
;             PG8_WAIT_V(6); PG8_BAR; PG8_MMA(1, 1, At, B1); PG8_BAR;
;             PG8_LDB(B0, 1, 0); PG8_SCHED; PG8_LDA(At, 1, 0); PG8_STAGE(PG8_SA(0, 1), a2 + hstepA, voffA);
;             PG8_WAIT_L(8); PG8_BAR; PG8_WAIT_L(0); PG8_MMA(0, 0, At, B0); PG8_BAR; PG8_SCHED;
;             PG8_LDB(B1, 1, 1); PG8_STAGE(PG8_SB(1, 0), b3, voffB);
	s_waitcnt lgkmcnt(0)
	s_setprio 0
	s_waitcnt lgkmcnt(0)
	v_mfma_f32_16x16x32_bf16 v[62:65], v[148:151], v[164:167], 0
	v_mfma_f32_16x16x32_bf16 v[58:61], v[156:159], v[164:167], 0
	v_mfma_f32_16x16x32_bf16 v[54:57], v[148:151], v[192:195], 0
	v_mfma_f32_16x16x32_bf16 v[50:53], v[156:159], v[192:195], 0
	v_mfma_f32_16x16x32_bf16 v[38:41], v[148:151], v[200:203], 0
	v_mfma_f32_16x16x32_bf16 v[34:37], v[156:159], v[200:203], 0
	v_mfma_f32_16x16x32_bf16 v[22:25], v[148:151], v[208:211], 0
	v_mfma_f32_16x16x32_bf16 v[18:21], v[156:159], v[208:211], 0
	v_mfma_f32_16x16x32_bf16 v[62:65], v[152:155], v[168:171], v[62:65]
	v_mfma_f32_16x16x32_bf16 v[58:61], v[160:163], v[168:171], v[58:61]
	v_mfma_f32_16x16x32_bf16 v[54:57], v[152:155], v[196:199], v[54:57]
	v_mfma_f32_16x16x32_bf16 v[50:53], v[160:163], v[196:199], v[50:53]
	v_mfma_f32_16x16x32_bf16 v[38:41], v[152:155], v[204:207], v[38:41]
	v_mfma_f32_16x16x32_bf16 v[34:37], v[160:163], v[204:207], v[34:37]
	v_mfma_f32_16x16x32_bf16 v[22:25], v[152:155], v[212:215], v[22:25]
	v_mfma_f32_16x16x32_bf16 v[18:21], v[160:163], v[212:215], v[18:21]
	s_setprio 1
	s_barrier
	s_add_u32 s56, s22, 0x40000
	s_addc_u32 s57, s23, 0
	s_add_i32 s58, s59, s26
	v_lshl_add_u64 v[148:149], s[56:57], 0, v[0:1]
	s_mov_b32 m0, s58
	s_nop 0
	global_load_lds_dwordx4 v[148:149], off
	v_lshl_add_u64 v[148:149], s[56:57], 0, v[130:131]
	s_add_i32 m0, s58, 0x2000
	s_nop 0
	global_load_lds_dwordx4 v[148:149], off
	s_waitcnt vmcnt(6)
	s_barrier
	s_setprio 0
	v_mfma_f32_16x16x32_bf16 v[46:49], v[216:219], v[164:167], 0
	v_mfma_f32_16x16x32_bf16 v[42:45], v[224:227], v[164:167], 0
	v_mfma_f32_16x16x32_bf16 v[30:33], v[216:219], v[192:195], 0
	v_mfma_f32_16x16x32_bf16 v[26:29], v[224:227], v[192:195], 0
	v_mfma_f32_16x16x32_bf16 v[14:17], v[216:219], v[200:203], 0
	v_mfma_f32_16x16x32_bf16 v[10:13], v[224:227], v[200:203], 0
	v_mfma_f32_16x16x32_bf16 v[6:9], v[216:219], v[208:211], 0
	v_mfma_f32_16x16x32_bf16 v[2:5], v[224:227], v[208:211], 0
	v_mfma_f32_16x16x32_bf16 v[46:49], v[220:223], v[168:171], v[46:49]
	v_mfma_f32_16x16x32_bf16 v[42:45], v[228:231], v[168:171], v[42:45]
	v_mfma_f32_16x16x32_bf16 v[30:33], v[220:223], v[196:199], v[30:33]
	v_mfma_f32_16x16x32_bf16 v[26:29], v[228:231], v[196:199], v[26:29]
	v_mfma_f32_16x16x32_bf16 v[14:17], v[220:223], v[204:207], v[14:17]
	v_mfma_f32_16x16x32_bf16 v[10:13], v[228:231], v[204:207], v[10:13]
	v_mfma_f32_16x16x32_bf16 v[6:9], v[220:223], v[212:215], v[6:9]
	v_mfma_f32_16x16x32_bf16 v[2:5], v[228:231], v[212:215], v[2:5]
	s_setprio 1
	s_add_i32 s56, 0, 0x18000
	v_add_u32_e32 v160, s56, v145
	s_barrier
	ds_read_b128 v[148:151], v160
	ds_read_b128 v[152:155], v160 offset:1024
	ds_read_b128 v[156:159], v160 offset:2048
	ds_read_b128 v[160:163], v160 offset:3072
	s_add_u32 s30, s30, 0x40000
	s_addc_u32 s31, s31, 0
	s_mov_b32 m0, s35
	v_lshl_add_u64 v[216:217], s[30:31], 0, v[134:135]
	ds_read_b128 v[164:167], v147 offset:32768
	ds_read_b128 v[168:171], v147 offset:33792
	ds_read_b128 v[192:195], v147 offset:34816
	ds_read_b128 v[196:199], v147 offset:35840
	ds_read_b128 v[200:203], v147 offset:36864
	ds_read_b128 v[204:207], v147 offset:37888
	ds_read_b128 v[208:211], v147 offset:38912
	ds_read_b128 v[212:215], v147 offset:39936
	global_load_lds_dwordx4 v[216:217], off
	v_lshl_add_u64 v[216:217], s[30:31], 0, v[132:133]
	s_mov_b32 m0, s36
	s_nop 0
	global_load_lds_dwordx4 v[216:217], off
	s_waitcnt lgkmcnt(8)
	s_barrier
	s_waitcnt lgkmcnt(0)
	s_setprio 0
	s_waitcnt lgkmcnt(0)
	v_mfma_f32_16x16x32_bf16 v[126:129], v[148:151], v[164:167], v[126:129]
	v_mfma_f32_16x16x32_bf16 v[122:125], v[156:159], v[164:167], v[122:125]
	v_mfma_f32_16x16x32_bf16 v[118:121], v[148:151], v[192:195], v[118:121]
	v_mfma_f32_16x16x32_bf16 v[114:117], v[156:159], v[192:195], v[114:117]
	v_mfma_f32_16x16x32_bf16 v[102:105], v[148:151], v[200:203], v[102:105]
	v_mfma_f32_16x16x32_bf16 v[98:101], v[156:159], v[200:203], v[98:101]
	v_mfma_f32_16x16x32_bf16 v[86:89], v[148:151], v[208:211], v[86:89]
	v_mfma_f32_16x16x32_bf16 v[82:85], v[156:159], v[208:211], v[82:85]
	v_mfma_f32_16x16x32_bf16 v[126:129], v[152:155], v[168:171], v[126:129]
	v_mfma_f32_16x16x32_bf16 v[122:125], v[160:163], v[168:171], v[122:125]
	v_mfma_f32_16x16x32_bf16 v[118:121], v[152:155], v[196:199], v[118:121]
	v_mfma_f32_16x16x32_bf16 v[114:117], v[160:163], v[196:199], v[114:117]
	v_mfma_f32_16x16x32_bf16 v[102:105], v[152:155], v[204:207], v[102:105]
	v_mfma_f32_16x16x32_bf16 v[98:101], v[160:163], v[204:207], v[98:101]
	v_mfma_f32_16x16x32_bf16 v[86:89], v[152:155], v[212:215], v[86:89]
	v_mfma_f32_16x16x32_bf16 v[82:85], v[160:163], v[212:215], v[82:85]
	s_setprio 1
	s_barrier
	s_add_i32 s30, 0, 0x1c000
	s_add_i32 s31, s56, s26
	v_add_u32_e32 v228, s30, v145
	v_lshl_add_u64 v[172:173], v[172:173], 0, s[18:19]
	s_mov_b32 m0, s31
	ds_read_b128 v[216:219], v228
	ds_read_b128 v[220:223], v228 offset:1024
	ds_read_b128 v[224:227], v228 offset:2048
	ds_read_b128 v[228:231], v228 offset:3072
	global_load_lds_dwordx4 v[172:173], off
	v_lshl_add_u64 v[172:173], v[232:233], 0, s[18:19]
	s_add_i32 m0, s31, 0x2000
	s_nop 0
	global_load_lds_dwordx4 v[172:173], off
	s_barrier
; #define PG8_STAGE(bufoff, gbase, voff) do { _Pragma("unroll") for (int _i = 0; _i < 2; ++_i) \
;         __builtin_amdgcn_global_load_lds((const unsigned*)((const char*)(gbase) + (voff)[_i]), (LAS unsigned*)(lds + (bufoff) + ldsw + _i * 8192), 16, 0, 0); } while (0)
; #define PG8_LDA(dst, b, h) do { _Pragma("unroll") for (int m = 0; m < 4; ++m) _Pragma("unroll") for (int k = 0; k < 2; ++k) dst[m][k] = *(const LAS bf16x8*)(lds + PG8_SA(b, h) + aoff + m * 2048 + k * 1024); } while (0)
; #define PG8_MMA(ai, bj, At, Bt_) do { __builtin_amdgcn_s_setprio(1); _Pragma("unroll") for (int m = 0; m < 4; ++m) _Pragma("unroll") for (int n = 0; n < 2; ++n) _Pragma("unroll") for (int k = 0; k < 2; ++k) \
;         acc[ai][bj][m][n] = __builtin_amdgcn_mfma_f32_16x16x32_bf16(Bt_[n][k], At[m][k], acc[ai][bj][m][n], 0, 0, 0); __builtin_amdgcn_s_setprio(0); } while (0)
; #define PG8_WAIT_V(n) asm volatile("s_waitcnt vmcnt(" #n ")" ::: "memory")
; #define PG8_WAIT_L(n) asm volatile("s_waitcnt lgkmcnt(" #n ")" ::: "memory")
; #define PG8_BAR __builtin_amdgcn_s_barrier()
; #define PG8_SCHED __builtin_amdgcn_sched_barrier(0)
; template <bool REMAP>
; DI void gemm_phase(LAS unsigned char* lds, const u16* A, int lda, const u16* Bt, int K, u16* O, int ldc, int nunits) {
;     ...
;             PG8_BAR; PG8_WAIT_L(0); PG8_MMA(0, 1, At, B1); PG8_BAR;
;             PG8_LDA(At, 1, 1); PG8_STAGE(PG8_SA(1, 0), a3, voffA);
;             PG8_BAR; PG8_WAIT_L(0); PG8_MMA(1, 0, At, B0); PG8_BAR; PG8_SCHED;
;             PG8_STAGE(PG8_SB(1, 1), b3 + hstepB, voffB);
;             PG8_WAIT_V(6); PG8_BAR; PG8_MMA(1, 1, At, B1); PG8_BAR;
	s_waitcnt lgkmcnt(0)
	s_setprio 0
	s_waitcnt lgkmcnt(0)
	v_mfma_f32_16x16x32_bf16 v[110:113], v[216:219], v[164:167], v[110:113]
	v_mfma_f32_16x16x32_bf16 v[106:109], v[224:227], v[164:167], v[106:109]
	v_mfma_f32_16x16x32_bf16 v[94:97], v[216:219], v[192:195], v[94:97]
	v_mfma_f32_16x16x32_bf16 v[90:93], v[224:227], v[192:195], v[90:93]
	v_mfma_f32_16x16x32_bf16 v[78:81], v[216:219], v[200:203], v[78:81]
	v_mfma_f32_16x16x32_bf16 v[74:77], v[224:227], v[200:203], v[74:77]
	v_mfma_f32_16x16x32_bf16 v[70:73], v[216:219], v[208:211], v[70:73]
	v_mfma_f32_16x16x32_bf16 v[66:69], v[224:227], v[208:211], v[66:69]
	v_mfma_f32_16x16x32_bf16 v[110:113], v[220:223], v[168:171], v[110:113]
	v_mfma_f32_16x16x32_bf16 v[106:109], v[228:231], v[168:171], v[106:109]
	v_mfma_f32_16x16x32_bf16 v[94:97], v[220:223], v[196:199], v[94:97]
	v_mfma_f32_16x16x32_bf16 v[90:93], v[228:231], v[196:199], v[90:93]
	v_mfma_f32_16x16x32_bf16 v[78:81], v[220:223], v[204:207], v[78:81]
	v_mfma_f32_16x16x32_bf16 v[74:77], v[228:231], v[204:207], v[74:77]
	v_mfma_f32_16x16x32_bf16 v[70:73], v[220:223], v[212:215], v[70:73]
	v_mfma_f32_16x16x32_bf16 v[66:69], v[228:231], v[212:215], v[66:69]
	s_setprio 1
	s_mov_b32 m0, s37
	v_lshl_add_u64 v[172:173], s[28:29], 0, v[134:135]
	s_barrier
	ds_read_b128 v[164:167], v147 offset:49152
	ds_read_b128 v[168:171], v147 offset:50176
	ds_read_b128 v[192:195], v147 offset:51200
	ds_read_b128 v[196:199], v147 offset:52224
	ds_read_b128 v[200:203], v147 offset:53248
	ds_read_b128 v[204:207], v147 offset:54272
	ds_read_b128 v[208:211], v147 offset:55296
	ds_read_b128 v[212:215], v147 offset:56320
	global_load_lds_dwordx4 v[172:173], off
	v_lshl_add_u64 v[172:173], s[28:29], 0, v[132:133]
	s_mov_b32 m0, s38
	s_nop 0
	global_load_lds_dwordx4 v[172:173], off
	s_barrier
	s_waitcnt lgkmcnt(0)
	s_setprio 0
	s_waitcnt lgkmcnt(0)
	v_mfma_f32_16x16x32_bf16 v[62:65], v[148:151], v[164:167], v[62:65]
	v_mfma_f32_16x16x32_bf16 v[58:61], v[156:159], v[164:167], v[58:61]
	v_mfma_f32_16x16x32_bf16 v[54:57], v[148:151], v[192:195], v[54:57]
	v_mfma_f32_16x16x32_bf16 v[50:53], v[156:159], v[192:195], v[50:53]
	v_mfma_f32_16x16x32_bf16 v[38:41], v[148:151], v[200:203], v[38:41]
	v_mfma_f32_16x16x32_bf16 v[34:37], v[156:159], v[200:203], v[34:37]
	v_mfma_f32_16x16x32_bf16 v[22:25], v[148:151], v[208:211], v[22:25]
	v_mfma_f32_16x16x32_bf16 v[18:21], v[156:159], v[208:211], v[18:21]
	v_mfma_f32_16x16x32_bf16 v[62:65], v[152:155], v[168:171], v[62:65]
	v_mfma_f32_16x16x32_bf16 v[58:61], v[160:163], v[168:171], v[58:61]
	v_mfma_f32_16x16x32_bf16 v[54:57], v[152:155], v[196:199], v[54:57]
	v_mfma_f32_16x16x32_bf16 v[50:53], v[160:163], v[196:199], v[50:53]
	v_mfma_f32_16x16x32_bf16 v[38:41], v[152:155], v[204:207], v[38:41]
	v_mfma_f32_16x16x32_bf16 v[34:37], v[160:163], v[204:207], v[34:37]
	v_mfma_f32_16x16x32_bf16 v[22:25], v[152:155], v[212:215], v[22:25]
	v_mfma_f32_16x16x32_bf16 v[18:21], v[160:163], v[212:215], v[18:21]
	s_setprio 1
	s_barrier
	s_add_u32 s22, s22, 0x40080
	s_addc_u32 s23, s23, 0
	s_add_i32 s28, s30, s26
	v_lshl_add_u64 v[148:149], s[22:23], 0, v[0:1]
	s_mov_b32 m0, s28
	s_nop 0
	global_load_lds_dwordx4 v[148:149], off
	v_lshl_add_u64 v[148:149], s[22:23], 0, v[130:131]
	s_add_i32 m0, s28, 0x2000
	s_nop 0
	global_load_lds_dwordx4 v[148:149], off
	s_waitcnt vmcnt(6)
	s_barrier
	s_setprio 0
	v_mfma_f32_16x16x32_bf16 v[46:49], v[216:219], v[164:167], v[46:49]
	v_mfma_f32_16x16x32_bf16 v[42:45], v[224:227], v[164:167], v[42:45]
	v_mfma_f32_16x16x32_bf16 v[30:33], v[216:219], v[192:195], v[30:33]
	v_mfma_f32_16x16x32_bf16 v[26:29], v[224:227], v[192:195], v[26:29]
	v_mfma_f32_16x16x32_bf16 v[14:17], v[216:219], v[200:203], v[14:17]
	v_mfma_f32_16x16x32_bf16 v[10:13], v[224:227], v[200:203], v[10:13]
	v_mfma_f32_16x16x32_bf16 v[6:9], v[216:219], v[208:211], v[6:9]
	v_mfma_f32_16x16x32_bf16 v[2:5], v[224:227], v[208:211], v[2:5]
	v_mfma_f32_16x16x32_bf16 v[46:49], v[220:223], v[168:171], v[46:49]
	v_mfma_f32_16x16x32_bf16 v[42:45], v[228:231], v[168:171], v[42:45]
	v_mfma_f32_16x16x32_bf16 v[30:33], v[220:223], v[196:199], v[30:33]
	v_mfma_f32_16x16x32_bf16 v[26:29], v[228:231], v[196:199], v[26:29]
	v_mfma_f32_16x16x32_bf16 v[14:17], v[220:223], v[204:207], v[14:17]
	v_mfma_f32_16x16x32_bf16 v[10:13], v[228:231], v[204:207], v[10:13]
	v_mfma_f32_16x16x32_bf16 v[6:9], v[220:223], v[212:215], v[6:9]
	v_mfma_f32_16x16x32_bf16 v[2:5], v[228:231], v[212:215], v[2:5]
	s_setprio 1
	s_add_i32 s55, s55, 2
	s_add_u32 s20, s20, 0x100
	s_addc_u32 s21, s21, 0
	s_cmp_gt_u32 s55, 13
	s_barrier
; #define PG8_STAGE(bufoff, gbase, voff) do { _Pragma("unroll") for (int _i = 0; _i < 2; ++_i) \
;         __builtin_amdgcn_global_load_lds((const unsigned*)((const char*)(gbase) + (voff)[_i]), (LAS unsigned*)(lds + (bufoff) + ldsw + _i * 8192), 16, 0, 0); } while (0)
; #define PG8_LDA(dst, b, h) do { _Pragma("unroll") for (int m = 0; m < 4; ++m) _Pragma("unroll") for (int k = 0; k < 2; ++k) dst[m][k] = *(const LAS bf16x8*)(lds + PG8_SA(b, h) + aoff + m * 2048 + k * 1024); } while (0)
; #define PG8_LDB(dst, b, h) do { _Pragma("unroll") for (int n = 0; n < 2; ++n) _Pragma("unroll") for (int k = 0; k < 2; ++k) dst[n][k] = *(const LAS bf16x8*)(lds + PG8_SB(b, h) + boff + n * 2048 + k * 1024); } while (0)
; #define PG8_MMA(ai, bj, At, Bt_) do { __builtin_amdgcn_s_setprio(1); _Pragma("unroll") for (int m = 0; m < 4; ++m) _Pragma("unroll") for (int n = 0; n < 2; ++n) _Pragma("unroll") for (int k = 0; k < 2; ++k) \
;         acc[ai][bj][m][n] = __builtin_amdgcn_mfma_f32_16x16x32_bf16(Bt_[n][k], At[m][k], acc[ai][bj][m][n], 0, 0, 0); __builtin_amdgcn_s_setprio(0); } while (0)
; #define PG8_WAIT_L(n) asm volatile("s_waitcnt lgkmcnt(" #n ")" ::: "memory")
; #define PG8_BAR __builtin_amdgcn_s_barrier()
; #define PG8_SCHED __builtin_amdgcn_sched_barrier(0)
; template <bool REMAP>
; DI void gemm_phase(LAS unsigned char* lds, const u16* A, int lda, const u16* Bt, int K, u16* O, int ldc, int nunits) {
;     ...
;             PG8_LDB(B0, 0, 0); PG8_SCHED; PG8_LDA(At, 0, 0); PG8_STAGE(PG8_SA(1, 1), a1 + hstepA, voffA);
;             PG8_WAIT_L(8); PG8_BAR; PG8_WAIT_L(0); PG8_MMA(0, 0, At, B0); PG8_BAR; PG8_SCHED;
;             PG8_LDB(B1, 0, 1); PG8_STAGE(PG8_SB(0, 0), b2, voffB);
;             PG8_BAR; PG8_WAIT_L(0); PG8_MMA(0, 1, At, B1); PG8_BAR;
;             PG8_LDA(At, 0, 1); PG8_STAGE(PG8_SA(0, 0), a2, voffA);
;             PG8_BAR; PG8_WAIT_L(0); PG8_MMA(1, 0, At, B0); PG8_BAR; PG8_SCHED;
.LBB0_137:
	s_add_u32 s22, s10, s20
	s_addc_u32 s23, s11, s21
	s_add_u32 s30, s22, 0x100
	s_addc_u32 s31, s23, 0
	s_add_u32 s56, s51, s20
	s_addc_u32 s57, s54, s21
	s_add_u32 s22, s22, 0x180
	s_addc_u32 s23, s23, 0
	s_add_i32 s58, 0, 0x10000
	v_add_u32_e32 v160, s58, v145
	ds_read_b128 v[148:151], v160
	ds_read_b128 v[152:155], v160 offset:1024
	ds_read_b128 v[156:159], v160 offset:2048
	ds_read_b128 v[160:163], v160 offset:3072
	s_cmpk_eq_i32 s20, 0x700
	s_cselect_b32 s29, s50, s23
	s_cselect_b32 s28, s49, s22
	s_cselect_b32 s23, s7, s57
	s_cselect_b32 s22, s47, s56
	s_cselect_b32 s31, s5, s31
	s_cselect_b32 s30, s46, s30
	v_lshl_add_u64 v[172:173], v[142:143], 0, s[20:21]
	s_add_i32 m0, s27, 0xc000
	ds_read_b128 v[164:167], v147
	ds_read_b128 v[168:171], v147 offset:1024
	ds_read_b128 v[192:195], v147 offset:2048
	ds_read_b128 v[196:199], v147 offset:3072
	ds_read_b128 v[200:203], v147 offset:4096
	ds_read_b128 v[204:207], v147 offset:5120
	ds_read_b128 v[208:211], v147 offset:6144
	ds_read_b128 v[212:215], v147 offset:7168
	global_load_lds_dwordx4 v[172:173], off
	v_lshl_add_u64 v[172:173], v[140:141], 0, s[20:21]
	s_add_i32 m0, s27, 0xe000
	s_nop 0
	global_load_lds_dwordx4 v[172:173], off
	s_waitcnt lgkmcnt(8)
	s_barrier
	s_waitcnt lgkmcnt(0)
	s_setprio 0
	s_waitcnt lgkmcnt(0)
	v_mfma_f32_16x16x32_bf16 v[126:129], v[148:151], v[164:167], v[126:129]
	v_mfma_f32_16x16x32_bf16 v[122:125], v[156:159], v[164:167], v[122:125]
	v_mfma_f32_16x16x32_bf16 v[118:121], v[148:151], v[192:195], v[118:121]
	v_mfma_f32_16x16x32_bf16 v[114:117], v[156:159], v[192:195], v[114:117]
	v_mfma_f32_16x16x32_bf16 v[102:105], v[148:151], v[200:203], v[102:105]
	v_mfma_f32_16x16x32_bf16 v[98:101], v[156:159], v[200:203], v[98:101]
	v_mfma_f32_16x16x32_bf16 v[86:89], v[148:151], v[208:211], v[86:89]
	v_mfma_f32_16x16x32_bf16 v[82:85], v[156:159], v[208:211], v[82:85]
	v_mfma_f32_16x16x32_bf16 v[126:129], v[152:155], v[168:171], v[126:129]
	v_mfma_f32_16x16x32_bf16 v[122:125], v[160:163], v[168:171], v[122:125]
	v_mfma_f32_16x16x32_bf16 v[118:121], v[152:155], v[196:199], v[118:121]
	v_mfma_f32_16x16x32_bf16 v[114:117], v[160:163], v[196:199], v[114:117]
	v_mfma_f32_16x16x32_bf16 v[102:105], v[152:155], v[204:207], v[102:105]
	v_mfma_f32_16x16x32_bf16 v[98:101], v[160:163], v[204:207], v[98:101]
	v_mfma_f32_16x16x32_bf16 v[86:89], v[152:155], v[212:215], v[86:89]
	v_mfma_f32_16x16x32_bf16 v[82:85], v[160:163], v[212:215], v[82:85]
	s_setprio 1
	s_barrier
	s_add_i32 s59, 0, 0x14000
	v_add_u32_e32 v172, s59, v145
	s_add_i32 s56, s58, s26
	ds_read_b128 v[216:219], v172
	ds_read_b128 v[220:223], v172 offset:1024
	ds_read_b128 v[224:227], v172 offset:2048
	ds_read_b128 v[228:231], v172 offset:3072
	v_lshl_add_u64 v[172:173], s[22:23], 0, v[0:1]
	s_mov_b32 m0, s56
	v_lshl_add_u64 v[232:233], s[22:23], 0, v[130:131]
	global_load_lds_dwordx4 v[172:173], off
	s_add_i32 m0, s56, 0x2000
	s_nop 0
	global_load_lds_dwordx4 v[232:233], off
	s_barrier
	s_waitcnt lgkmcnt(0)
	s_setprio 0
	s_waitcnt lgkmcnt(0)
	v_mfma_f32_16x16x32_bf16 v[110:113], v[216:219], v[164:167], v[110:113]
	v_mfma_f32_16x16x32_bf16 v[106:109], v[224:227], v[164:167], v[106:109]
	v_mfma_f32_16x16x32_bf16 v[94:97], v[216:219], v[192:195], v[94:97]
	v_mfma_f32_16x16x32_bf16 v[90:93], v[224:227], v[192:195], v[90:93]
	v_mfma_f32_16x16x32_bf16 v[78:81], v[216:219], v[200:203], v[78:81]
	v_mfma_f32_16x16x32_bf16 v[74:77], v[224:227], v[200:203], v[74:77]
	v_mfma_f32_16x16x32_bf16 v[70:73], v[216:219], v[208:211], v[70:73]
	v_mfma_f32_16x16x32_bf16 v[66:69], v[224:227], v[208:211], v[66:69]
	v_mfma_f32_16x16x32_bf16 v[110:113], v[220:223], v[168:171], v[110:113]
	v_mfma_f32_16x16x32_bf16 v[106:109], v[228:231], v[168:171], v[106:109]
	v_mfma_f32_16x16x32_bf16 v[94:97], v[220:223], v[196:199], v[94:97]
	v_mfma_f32_16x16x32_bf16 v[90:93], v[228:231], v[196:199], v[90:93]
	v_mfma_f32_16x16x32_bf16 v[78:81], v[220:223], v[204:207], v[78:81]
	v_mfma_f32_16x16x32_bf16 v[74:77], v[228:231], v[204:207], v[74:77]
	v_mfma_f32_16x16x32_bf16 v[70:73], v[220:223], v[212:215], v[70:73]
	v_mfma_f32_16x16x32_bf16 v[66:69], v[228:231], v[212:215], v[66:69]
	s_setprio 1
	s_mov_b32 m0, s27
	v_lshl_add_u64 v[234:235], s[30:31], 0, v[134:135]
	s_barrier
	ds_read_b128 v[164:167], v147 offset:16384
	ds_read_b128 v[168:171], v147 offset:17408
	ds_read_b128 v[192:195], v147 offset:18432
	ds_read_b128 v[196:199], v147 offset:19456
	ds_read_b128 v[200:203], v147 offset:20480
	ds_read_b128 v[204:207], v147 offset:21504
	ds_read_b128 v[208:211], v147 offset:22528
	ds_read_b128 v[212:215], v147 offset:23552
	global_load_lds_dwordx4 v[234:235], off
	v_lshl_add_u64 v[234:235], s[30:31], 0, v[132:133]
	s_mov_b32 m0, s34
	s_nop 0
	global_load_lds_dwordx4 v[234:235], off
	s_barrier
	s_waitcnt lgkmcnt(0)
	s_setprio 0
	s_waitcnt lgkmcnt(0)
	v_mfma_f32_16x16x32_bf16 v[62:65], v[148:151], v[164:167], v[62:65]
	v_mfma_f32_16x16x32_bf16 v[58:61], v[156:159], v[164:167], v[58:61]
	v_mfma_f32_16x16x32_bf16 v[54:57], v[148:151], v[192:195], v[54:57]
	v_mfma_f32_16x16x32_bf16 v[50:53], v[156:159], v[192:195], v[50:53]
	v_mfma_f32_16x16x32_bf16 v[38:41], v[148:151], v[200:203], v[38:41]
	v_mfma_f32_16x16x32_bf16 v[34:37], v[156:159], v[200:203], v[34:37]
	v_mfma_f32_16x16x32_bf16 v[22:25], v[148:151], v[208:211], v[22:25]
	v_mfma_f32_16x16x32_bf16 v[18:21], v[156:159], v[208:211], v[18:21]
	v_mfma_f32_16x16x32_bf16 v[62:65], v[152:155], v[168:171], v[62:65]
	v_mfma_f32_16x16x32_bf16 v[58:61], v[160:163], v[168:171], v[58:61]
	v_mfma_f32_16x16x32_bf16 v[54:57], v[152:155], v[196:199], v[54:57]
	v_mfma_f32_16x16x32_bf16 v[50:53], v[160:163], v[196:199], v[50:53]
	v_mfma_f32_16x16x32_bf16 v[38:41], v[152:155], v[204:207], v[38:41]
	v_mfma_f32_16x16x32_bf16 v[34:37], v[160:163], v[204:207], v[34:37]
	v_mfma_f32_16x16x32_bf16 v[22:25], v[152:155], v[212:215], v[22:25]
	v_mfma_f32_16x16x32_bf16 v[18:21], v[160:163], v[212:215], v[18:21]
	s_setprio 1
	s_barrier
; #define PG8_STAGE(bufoff, gbase, voff) do { _Pragma("unroll") for (int _i = 0; _i < 2; ++_i) \
;         __builtin_amdgcn_global_load_lds((const unsigned*)((const char*)(gbase) + (voff)[_i]), (LAS unsigned*)(lds + (bufoff) + ldsw + _i * 8192), 16, 0, 0); } while (0)
; #define PG8_LDA(dst, b, h) do { _Pragma("unroll") for (int m = 0; m < 4; ++m) _Pragma("unroll") for (int k = 0; k < 2; ++k) dst[m][k] = *(const LAS bf16x8*)(lds + PG8_SA(b, h) + aoff + m * 2048 + k * 1024); } while (0)
; #define PG8_LDB(dst, b, h) do { _Pragma("unroll") for (int n = 0; n < 2; ++n) _Pragma("unroll") for (int k = 0; k < 2; ++k) dst[n][k] = *(const LAS bf16x8*)(lds + PG8_SB(b, h) + boff + n * 2048 + k * 1024); } while (0)
; #define PG8_MMA(ai, bj, At, Bt_) do { __builtin_amdgcn_s_setprio(1); _Pragma("unroll") for (int m = 0; m < 4; ++m) _Pragma("unroll") for (int n = 0; n < 2; ++n) _Pragma("unroll") for (int k = 0; k < 2; ++k) \
;         acc[ai][bj][m][n] = __builtin_amdgcn_mfma_f32_16x16x32_bf16(Bt_[n][k], At[m][k], acc[ai][bj][m][n], 0, 0, 0); __builtin_amdgcn_s_setprio(0); } while (0)
; #define PG8_WAIT_V(n) asm volatile("s_waitcnt vmcnt(" #n ")" ::: "memory")
; #define PG8_WAIT_L(n) asm volatile("s_waitcnt lgkmcnt(" #n ")" ::: "memory")
; #define PG8_BAR __builtin_amdgcn_s_barrier()
; #define PG8_SCHED __builtin_amdgcn_sched_barrier(0)
; template <bool REMAP>
; DI void gemm_phase(LAS unsigned char* lds, const u16* A, int lda, const u16* Bt, int K, u16* O, int ldc, int nunits) {
;     ...
;             PG8_WAIT_V(6); PG8_BAR; PG8_MMA(1, 1, At, B1); PG8_BAR;
;             PG8_LDB(B0, 1, 0); PG8_SCHED; PG8_LDA(At, 1, 0); PG8_STAGE(PG8_SA(0, 1), a2 + hstepA, voffA);
;             PG8_WAIT_L(8); PG8_BAR; PG8_WAIT_L(0); PG8_MMA(0, 0, At, B0); PG8_BAR; PG8_SCHED;
;             PG8_LDB(B1, 1, 1); PG8_STAGE(PG8_SB(1, 0), b3, voffB);
;             PG8_BAR; PG8_WAIT_L(0); PG8_MMA(0, 1, At, B1); PG8_BAR;
;             PG8_LDA(At, 1, 1); PG8_STAGE(PG8_SA(1, 0), a3, voffA);
	s_add_u32 s56, s22, 0x40000
	s_addc_u32 s57, s23, 0
	s_add_i32 s58, s59, s26
	v_lshl_add_u64 v[148:149], s[56:57], 0, v[0:1]
	s_mov_b32 m0, s58
	s_nop 0
	global_load_lds_dwordx4 v[148:149], off
	v_lshl_add_u64 v[148:149], s[56:57], 0, v[130:131]
	s_add_i32 m0, s58, 0x2000
	s_nop 0
	global_load_lds_dwordx4 v[148:149], off
	s_waitcnt vmcnt(6)
	s_barrier
	s_setprio 0
	v_mfma_f32_16x16x32_bf16 v[46:49], v[216:219], v[164:167], v[46:49]
	v_mfma_f32_16x16x32_bf16 v[42:45], v[224:227], v[164:167], v[42:45]
	v_mfma_f32_16x16x32_bf16 v[30:33], v[216:219], v[192:195], v[30:33]
	v_mfma_f32_16x16x32_bf16 v[26:29], v[224:227], v[192:195], v[26:29]
	v_mfma_f32_16x16x32_bf16 v[14:17], v[216:219], v[200:203], v[14:17]
	v_mfma_f32_16x16x32_bf16 v[10:13], v[224:227], v[200:203], v[10:13]
	v_mfma_f32_16x16x32_bf16 v[6:9], v[216:219], v[208:211], v[6:9]
	v_mfma_f32_16x16x32_bf16 v[2:5], v[224:227], v[208:211], v[2:5]
	v_mfma_f32_16x16x32_bf16 v[46:49], v[220:223], v[168:171], v[46:49]
	v_mfma_f32_16x16x32_bf16 v[42:45], v[228:231], v[168:171], v[42:45]
	v_mfma_f32_16x16x32_bf16 v[30:33], v[220:223], v[196:199], v[30:33]
	v_mfma_f32_16x16x32_bf16 v[26:29], v[228:231], v[196:199], v[26:29]
	v_mfma_f32_16x16x32_bf16 v[14:17], v[220:223], v[204:207], v[14:17]
	v_mfma_f32_16x16x32_bf16 v[10:13], v[228:231], v[204:207], v[10:13]
	v_mfma_f32_16x16x32_bf16 v[6:9], v[220:223], v[212:215], v[6:9]
	v_mfma_f32_16x16x32_bf16 v[2:5], v[228:231], v[212:215], v[2:5]
	s_setprio 1
	s_add_i32 s56, 0, 0x18000
	v_add_u32_e32 v160, s56, v145
	s_barrier
	ds_read_b128 v[148:151], v160
	ds_read_b128 v[152:155], v160 offset:1024
	ds_read_b128 v[156:159], v160 offset:2048
	ds_read_b128 v[160:163], v160 offset:3072
	s_add_u32 s30, s30, 0x40000
	s_addc_u32 s31, s31, 0
	s_mov_b32 m0, s35
	v_lshl_add_u64 v[216:217], s[30:31], 0, v[134:135]
	ds_read_b128 v[164:167], v147 offset:32768
	ds_read_b128 v[168:171], v147 offset:33792
	ds_read_b128 v[192:195], v147 offset:34816
	ds_read_b128 v[196:199], v147 offset:35840
	ds_read_b128 v[200:203], v147 offset:36864
	ds_read_b128 v[204:207], v147 offset:37888
	ds_read_b128 v[208:211], v147 offset:38912
	ds_read_b128 v[212:215], v147 offset:39936
	global_load_lds_dwordx4 v[216:217], off
	v_lshl_add_u64 v[216:217], s[30:31], 0, v[132:133]
	s_mov_b32 m0, s36
	s_nop 0
	global_load_lds_dwordx4 v[216:217], off
	s_waitcnt lgkmcnt(8)
	s_barrier
	s_waitcnt lgkmcnt(0)
	s_setprio 0
	s_waitcnt lgkmcnt(0)
	v_mfma_f32_16x16x32_bf16 v[126:129], v[148:151], v[164:167], v[126:129]
	v_mfma_f32_16x16x32_bf16 v[122:125], v[156:159], v[164:167], v[122:125]
	v_mfma_f32_16x16x32_bf16 v[118:121], v[148:151], v[192:195], v[118:121]
	v_mfma_f32_16x16x32_bf16 v[114:117], v[156:159], v[192:195], v[114:117]
	v_mfma_f32_16x16x32_bf16 v[102:105], v[148:151], v[200:203], v[102:105]
	v_mfma_f32_16x16x32_bf16 v[98:101], v[156:159], v[200:203], v[98:101]
	v_mfma_f32_16x16x32_bf16 v[86:89], v[148:151], v[208:211], v[86:89]
	v_mfma_f32_16x16x32_bf16 v[82:85], v[156:159], v[208:211], v[82:85]
	v_mfma_f32_16x16x32_bf16 v[126:129], v[152:155], v[168:171], v[126:129]
	v_mfma_f32_16x16x32_bf16 v[122:125], v[160:163], v[168:171], v[122:125]
	v_mfma_f32_16x16x32_bf16 v[118:121], v[152:155], v[196:199], v[118:121]
	v_mfma_f32_16x16x32_bf16 v[114:117], v[160:163], v[196:199], v[114:117]
	v_mfma_f32_16x16x32_bf16 v[102:105], v[152:155], v[204:207], v[102:105]
	v_mfma_f32_16x16x32_bf16 v[98:101], v[160:163], v[204:207], v[98:101]
	v_mfma_f32_16x16x32_bf16 v[86:89], v[152:155], v[212:215], v[86:89]
	v_mfma_f32_16x16x32_bf16 v[82:85], v[160:163], v[212:215], v[82:85]
	s_setprio 1
	s_barrier
	s_add_i32 s30, 0, 0x1c000
	s_add_i32 s31, s56, s26
	v_add_u32_e32 v228, s30, v145
	v_lshl_add_u64 v[172:173], v[172:173], 0, s[18:19]
	s_mov_b32 m0, s31
	ds_read_b128 v[216:219], v228
	ds_read_b128 v[220:223], v228 offset:1024
	ds_read_b128 v[224:227], v228 offset:2048
	ds_read_b128 v[228:231], v228 offset:3072
	global_load_lds_dwordx4 v[172:173], off
	v_lshl_add_u64 v[172:173], v[232:233], 0, s[18:19]
	s_add_i32 m0, s31, 0x2000
	s_nop 0
	global_load_lds_dwordx4 v[172:173], off
	s_barrier
	s_waitcnt lgkmcnt(0)
	s_setprio 0
	s_waitcnt lgkmcnt(0)
	v_mfma_f32_16x16x32_bf16 v[110:113], v[216:219], v[164:167], v[110:113]
	v_mfma_f32_16x16x32_bf16 v[106:109], v[224:227], v[164:167], v[106:109]
	v_mfma_f32_16x16x32_bf16 v[94:97], v[216:219], v[192:195], v[94:97]
	v_mfma_f32_16x16x32_bf16 v[90:93], v[224:227], v[192:195], v[90:93]
	v_mfma_f32_16x16x32_bf16 v[78:81], v[216:219], v[200:203], v[78:81]
	v_mfma_f32_16x16x32_bf16 v[74:77], v[224:227], v[200:203], v[74:77]
	v_mfma_f32_16x16x32_bf16 v[70:73], v[216:219], v[208:211], v[70:73]
	v_mfma_f32_16x16x32_bf16 v[66:69], v[224:227], v[208:211], v[66:69]
	v_mfma_f32_16x16x32_bf16 v[110:113], v[220:223], v[168:171], v[110:113]
	v_mfma_f32_16x16x32_bf16 v[106:109], v[228:231], v[168:171], v[106:109]
	v_mfma_f32_16x16x32_bf16 v[94:97], v[220:223], v[196:199], v[94:97]
	v_mfma_f32_16x16x32_bf16 v[90:93], v[228:231], v[196:199], v[90:93]
	v_mfma_f32_16x16x32_bf16 v[78:81], v[220:223], v[204:207], v[78:81]
	v_mfma_f32_16x16x32_bf16 v[74:77], v[228:231], v[204:207], v[74:77]
	v_mfma_f32_16x16x32_bf16 v[70:73], v[220:223], v[212:215], v[70:73]
	v_mfma_f32_16x16x32_bf16 v[66:69], v[228:231], v[212:215], v[66:69]
	s_setprio 1
	s_mov_b32 m0, s37
	v_lshl_add_u64 v[172:173], s[28:29], 0, v[134:135]
	s_barrier
	ds_read_b128 v[164:167], v147 offset:49152
	ds_read_b128 v[168:171], v147 offset:50176
	ds_read_b128 v[192:195], v147 offset:51200
	ds_read_b128 v[196:199], v147 offset:52224
	ds_read_b128 v[200:203], v147 offset:53248
	ds_read_b128 v[204:207], v147 offset:54272
	ds_read_b128 v[208:211], v147 offset:55296
	ds_read_b128 v[212:215], v147 offset:56320
	global_load_lds_dwordx4 v[172:173], off
	v_lshl_add_u64 v[172:173], s[28:29], 0, v[132:133]
	s_mov_b32 m0, s38
	s_nop 0
	global_load_lds_dwordx4 v[172:173], off
	s_barrier
; DI unsigned pk2(float lo, float hi) { fl2_t f = {lo, hi}; bf2_t b = __builtin_convertvector(f, bf2_t); return __builtin_bit_cast(unsigned, b); }
; #define PG8_STAGE(bufoff, gbase, voff) do { _Pragma("unroll") for (int _i = 0; _i < 2; ++_i) \
;         __builtin_amdgcn_global_load_lds((const unsigned*)((const char*)(gbase) + (voff)[_i]), (LAS unsigned*)(lds + (bufoff) + ldsw + _i * 8192), 16, 0, 0); } while (0)
; #define PG8_MMA(ai, bj, At, Bt_) do { __builtin_amdgcn_s_setprio(1); _Pragma("unroll") for (int m = 0; m < 4; ++m) _Pragma("unroll") for (int n = 0; n < 2; ++n) _Pragma("unroll") for (int k = 0; k < 2; ++k) \
;         acc[ai][bj][m][n] = __builtin_amdgcn_mfma_f32_16x16x32_bf16(Bt_[n][k], At[m][k], acc[ai][bj][m][n], 0, 0, 0); __builtin_amdgcn_s_setprio(0); } while (0)
; #define PG8_WAIT_V(n) asm volatile("s_waitcnt vmcnt(" #n ")" ::: "memory")
; #define PG8_WAIT_L(n) asm volatile("s_waitcnt lgkmcnt(" #n ")" ::: "memory")
; template <bool REMAP>
; DI void gemm_phase(LAS unsigned char* lds, const u16* A, int lda, const u16* Bt, int K, u16* O, int ldc, int nunits) {
;     ...
;             PG8_BAR; PG8_WAIT_L(0); PG8_MMA(1, 0, At, B0); PG8_BAR; PG8_SCHED;
;             PG8_STAGE(PG8_SB(1, 1), b3 + hstepB, voffB);
;             PG8_WAIT_V(6); PG8_BAR; PG8_MMA(1, 1, At, B1); PG8_BAR;
;         }
;         {
;             const int row0 = cur.pm * BM + wr * 64 + fr, col0 = cur.pn * BM + wc * 32 + 8 * fq;
; #pragma unroll
;             for (int ai = 0; ai < 2; ++ai)
; #pragma unroll
;                 for (int m = 0; m < 4; ++m) { u16* rowp = O + (size_t)(row0 + ai * HALF + m * 16) * ldc + col0;
; #pragma unroll
;                     for (int bj = 0; bj < 2; ++bj) { const f32x4 v0 = acc[ai][bj][m][0], v1 = acc[ai][bj][m][1];
;                         u32x4 w = {pk2(v0[0], v0[1]), pk2(v0[2], v0[3]), pk2(v1[0], v1[1]), pk2(v1[2], v1[3])};
;                         *(u32x4*)(rowp + bj * HALF) = w; } }
;         }
;         if (!has_next) break;
; #pragma unroll
;         for (int a = 0; a < 2; ++a)
; #pragma unroll
;             for (int b = 0; b < 2; ++b)
; #pragma unroll
;                 for (int m = 0; m < 4; ++m)
; #pragma unroll
;                     for (int n = 0; n < 2; ++n) acc[a][b][m][n] = (f32x4){0.f, 0.f, 0.f, 0.f};
;         cur = nxt; cA = nA; cB = nB; ++ui;
;     }
;     PG8_WAIT_V(0);
;     if (wr == 0) PG8_BAR;
;     PG8_BAR;
	s_waitcnt lgkmcnt(0)
	s_setprio 0
	s_waitcnt lgkmcnt(0)
	v_mfma_f32_16x16x32_bf16 v[62:65], v[148:151], v[164:167], v[62:65]
	v_mfma_f32_16x16x32_bf16 v[58:61], v[156:159], v[164:167], v[58:61]
	v_mfma_f32_16x16x32_bf16 v[54:57], v[148:151], v[192:195], v[54:57]
	v_mfma_f32_16x16x32_bf16 v[50:53], v[156:159], v[192:195], v[50:53]
	v_mfma_f32_16x16x32_bf16 v[38:41], v[148:151], v[200:203], v[38:41]
	v_mfma_f32_16x16x32_bf16 v[34:37], v[156:159], v[200:203], v[34:37]
	v_mfma_f32_16x16x32_bf16 v[22:25], v[148:151], v[208:211], v[22:25]
	v_mfma_f32_16x16x32_bf16 v[18:21], v[156:159], v[208:211], v[18:21]
	v_mfma_f32_16x16x32_bf16 v[62:65], v[152:155], v[168:171], v[62:65]
	v_mfma_f32_16x16x32_bf16 v[58:61], v[160:163], v[168:171], v[58:61]
	v_mfma_f32_16x16x32_bf16 v[54:57], v[152:155], v[196:199], v[54:57]
	v_mfma_f32_16x16x32_bf16 v[50:53], v[160:163], v[196:199], v[50:53]
	v_mfma_f32_16x16x32_bf16 v[38:41], v[152:155], v[204:207], v[38:41]
	v_mfma_f32_16x16x32_bf16 v[34:37], v[160:163], v[204:207], v[34:37]
	v_mfma_f32_16x16x32_bf16 v[22:25], v[152:155], v[212:215], v[22:25]
	v_mfma_f32_16x16x32_bf16 v[18:21], v[160:163], v[212:215], v[18:21]
	s_setprio 1
	s_barrier
	s_add_u32 s22, s22, 0x40080
	s_addc_u32 s23, s23, 0
	s_add_i32 s28, s30, s26
	v_lshl_add_u64 v[148:149], s[22:23], 0, v[0:1]
	s_mov_b32 m0, s28
	s_nop 0
	global_load_lds_dwordx4 v[148:149], off
	v_lshl_add_u64 v[148:149], s[22:23], 0, v[130:131]
	s_add_i32 m0, s28, 0x2000
	s_nop 0
	global_load_lds_dwordx4 v[148:149], off
	s_waitcnt vmcnt(6)
	s_barrier
	s_setprio 0
	v_mfma_f32_16x16x32_bf16 v[46:49], v[216:219], v[164:167], v[46:49]
	v_mfma_f32_16x16x32_bf16 v[42:45], v[224:227], v[164:167], v[42:45]
	v_mfma_f32_16x16x32_bf16 v[30:33], v[216:219], v[192:195], v[30:33]
	v_mfma_f32_16x16x32_bf16 v[26:29], v[224:227], v[192:195], v[26:29]
	v_mfma_f32_16x16x32_bf16 v[14:17], v[216:219], v[200:203], v[14:17]
	v_mfma_f32_16x16x32_bf16 v[10:13], v[224:227], v[200:203], v[10:13]
	v_mfma_f32_16x16x32_bf16 v[6:9], v[216:219], v[208:211], v[6:9]
	v_mfma_f32_16x16x32_bf16 v[2:5], v[224:227], v[208:211], v[2:5]
	v_mfma_f32_16x16x32_bf16 v[46:49], v[220:223], v[168:171], v[46:49]
	v_mfma_f32_16x16x32_bf16 v[42:45], v[228:231], v[168:171], v[42:45]
	v_mfma_f32_16x16x32_bf16 v[30:33], v[220:223], v[196:199], v[30:33]
	v_mfma_f32_16x16x32_bf16 v[26:29], v[228:231], v[196:199], v[26:29]
	v_mfma_f32_16x16x32_bf16 v[14:17], v[220:223], v[204:207], v[14:17]
	v_mfma_f32_16x16x32_bf16 v[10:13], v[228:231], v[204:207], v[10:13]
	v_mfma_f32_16x16x32_bf16 v[6:9], v[220:223], v[212:215], v[6:9]
	v_mfma_f32_16x16x32_bf16 v[2:5], v[228:231], v[212:215], v[2:5]
	s_setprio 1
	s_add_i32 s55, s55, 2
	s_add_u32 s20, s20, 0x100
	s_addc_u32 s21, s21, 0
	s_cmp_gt_u32 s55, 13
	s_barrier
	s_cbranch_scc0 .LBB0_137
	v_lshl_or_b32 v140, s40, 8, v146
	v_lshl_add_u32 v148, s41, 8, v144
	v_ashrrev_i32_e32 v141, 31, v140
	v_lshl_add_u64 v[140:141], v[140:141], 1, s[0:1]
	v_cvt_pk_bf16_f32 v70, v70, v71
	v_cvt_pk_bf16_f32 v71, v72, v73
	v_cvt_pk_bf16_f32 v72, v66, v67
	v_add_u32_e32 v66, 0x80, v148
	v_mad_i64_i32 v[142:143], s[10:11], v148, s52, v[140:141]
	v_cvt_pk_bf16_f32 v110, v110, v111
	v_cvt_pk_bf16_f32 v111, v112, v113
	v_cvt_pk_bf16_f32 v112, v106, v107
	v_cvt_pk_bf16_f32 v113, v108, v109
	v_or_b32_e32 v106, 16, v148
	v_mad_i64_i32 v[66:67], s[10:11], v66, s52, v[140:141]
	v_cvt_pk_bf16_f32 v46, v46, v47
	v_cvt_pk_bf16_f32 v47, v48, v49
	v_cvt_pk_bf16_f32 v48, v42, v43
	v_cvt_pk_bf16_f32 v49, v44, v45
	v_add_u32_e32 v42, 0x90, v148
	flat_store_dwordx4 v[142:143], v[110:113] offset:256
	v_cvt_pk_bf16_f32 v94, v94, v95
	v_cvt_pk_bf16_f32 v95, v96, v97
	v_mad_i64_i32 v[110:111], s[10:11], v106, s52, v[140:141]
	v_cvt_pk_bf16_f32 v96, v90, v91
	v_cvt_pk_bf16_f32 v97, v92, v93
	v_or_b32_e32 v90, 32, v148
	flat_store_dwordx4 v[66:67], v[46:49] offset:256
	v_cvt_pk_bf16_f32 v30, v30, v31
	v_cvt_pk_bf16_f32 v31, v32, v33
	v_mad_i64_i32 v[46:47], s[10:11], v42, s52, v[140:141]
	v_cvt_pk_bf16_f32 v32, v26, v27
	v_cvt_pk_bf16_f32 v33, v28, v29
	v_add_u32_e32 v26, 0xa0, v148
	flat_store_dwordx4 v[110:111], v[94:97] offset:256
	v_cvt_pk_bf16_f32 v78, v78, v79
	v_cvt_pk_bf16_f32 v79, v80, v81
	v_mad_i64_i32 v[94:95], s[10:11], v90, s52, v[140:141]
	v_cvt_pk_bf16_f32 v80, v74, v75
	v_cvt_pk_bf16_f32 v81, v76, v77
	v_or_b32_e32 v74, 48, v148
	flat_store_dwordx4 v[46:47], v[30:33] offset:256
	v_cvt_pk_bf16_f32 v14, v14, v15
	v_cvt_pk_bf16_f32 v15, v16, v17
	v_mad_i64_i32 v[30:31], s[10:11], v26, s52, v[140:141]
	v_cvt_pk_bf16_f32 v16, v10, v11
	v_cvt_pk_bf16_f32 v17, v12, v13
	v_add_u32_e32 v10, 0xb0, v148
	flat_store_dwordx4 v[94:95], v[78:81] offset:256
	flat_store_dwordx4 v[30:31], v[14:17] offset:256
	v_cvt_pk_bf16_f32 v126, v126, v127
	v_mad_i64_i32 v[78:79], s[10:11], v74, s52, v[140:141]
	v_mad_i64_i32 v[14:15], s[10:11], v10, s52, v[140:141]
	v_cvt_pk_bf16_f32 v127, v128, v129
	v_cvt_pk_bf16_f32 v128, v122, v123
	v_cvt_pk_bf16_f32 v129, v124, v125
	v_cvt_pk_bf16_f32 v106, v118, v119
	v_cvt_pk_bf16_f32 v107, v120, v121
	v_cvt_pk_bf16_f32 v108, v114, v115
	v_cvt_pk_bf16_f32 v109, v116, v117
	v_cvt_pk_bf16_f32 v90, v102, v103
	v_cvt_pk_bf16_f32 v91, v104, v105
	v_cvt_pk_bf16_f32 v92, v98, v99
	v_cvt_pk_bf16_f32 v93, v100, v101
	v_cvt_pk_bf16_f32 v74, v86, v87
	v_cvt_pk_bf16_f32 v75, v88, v89
	v_cvt_pk_bf16_f32 v76, v82, v83
	v_cvt_pk_bf16_f32 v77, v84, v85
	v_cvt_pk_bf16_f32 v73, v68, v69
	v_cvt_pk_bf16_f32 v62, v62, v63
	v_cvt_pk_bf16_f32 v63, v64, v65
	v_cvt_pk_bf16_f32 v64, v58, v59
	v_cvt_pk_bf16_f32 v65, v60, v61
	v_cvt_pk_bf16_f32 v42, v54, v55
	v_cvt_pk_bf16_f32 v43, v56, v57
	v_cvt_pk_bf16_f32 v44, v50, v51
	v_cvt_pk_bf16_f32 v45, v52, v53
	v_cvt_pk_bf16_f32 v26, v38, v39
	v_cvt_pk_bf16_f32 v27, v40, v41
	v_cvt_pk_bf16_f32 v28, v34, v35
	v_cvt_pk_bf16_f32 v29, v36, v37
	v_cvt_pk_bf16_f32 v10, v22, v23
	v_cvt_pk_bf16_f32 v11, v24, v25
	v_cvt_pk_bf16_f32 v12, v18, v19
	v_cvt_pk_bf16_f32 v13, v20, v21
	v_cvt_pk_bf16_f32 v6, v6, v7
	v_cvt_pk_bf16_f32 v7, v8, v9
	v_cvt_pk_bf16_f32 v8, v2, v3
	v_cvt_pk_bf16_f32 v9, v4, v5
	s_and_b64 vcc, exec, s[8:9]
	s_mov_b32 s40, s6
	s_mov_b32 s41, s4
	s_mov_b64 s[20:21], s[14:15]
	s_mov_b64 s[10:11], s[12:13]
	flat_store_dwordx4 v[142:143], v[126:129]
	flat_store_dwordx4 v[110:111], v[106:109]
	flat_store_dwordx4 v[94:95], v[90:93]
	flat_store_dwordx4 v[78:79], v[74:77]
	flat_store_dwordx4 v[78:79], v[70:73] offset:256
	flat_store_dwordx4 v[66:67], v[62:65]
	flat_store_dwordx4 v[46:47], v[42:45]
	flat_store_dwordx4 v[30:31], v[26:29]
	flat_store_dwordx4 v[14:15], v[10:13]
	flat_store_dwordx4 v[14:15], v[6:9] offset:256
	s_cbranch_vccz .LBB0_134
	s_waitcnt vmcnt(0)
	s_cmpk_gt_u32 s2, 0xff
	s_cbranch_scc1 .LBB0_141
	s_barrier

; #define PG8_STAGE(bufoff, gbase, voff) do { _Pragma("unroll") for (int _i = 0; _i < 2; ++_i) \
;         __builtin_amdgcn_global_load_lds((const unsigned*)((const char*)(gbase) + (voff)[_i]), (LAS unsigned*)(lds + (bufoff) + ldsw + _i * 8192), 16, 0, 0); } while (0)
; #define PG8_LDA(dst, b, h) do { _Pragma("unroll") for (int m = 0; m < 4; ++m) _Pragma("unroll") for (int k = 0; k < 2; ++k) dst[m][k] = *(const LAS bf16x8*)(lds + PG8_SA(b, h) + aoff + m * 2048 + k * 1024); } while (0)
; #define PG8_LDB(dst, b, h) do { _Pragma("unroll") for (int n = 0; n < 2; ++n) _Pragma("unroll") for (int k = 0; k < 2; ++k) dst[n][k] = *(const LAS bf16x8*)(lds + PG8_SB(b, h) + boff + n * 2048 + k * 1024); } while (0)
; #define PG8_MMA(ai, bj, At, Bt_) do { __builtin_amdgcn_s_setprio(1); _Pragma("unroll") for (int m = 0; m < 4; ++m) _Pragma("unroll") for (int n = 0; n < 2; ++n) _Pragma("unroll") for (int k = 0; k < 2; ++k) \
;         acc[ai][bj][m][n] = __builtin_amdgcn_mfma_f32_16x16x32_bf16(Bt_[n][k], At[m][k], acc[ai][bj][m][n], 0, 0, 0); __builtin_amdgcn_s_setprio(0); } while (0)
; #define PG8_WAIT_L(n) asm volatile("s_waitcnt lgkmcnt(" #n ")" ::: "memory")
; #define PG8_BAR __builtin_amdgcn_s_barrier()
; template <bool REMAP>
; DI void gemm_phase(LAS unsigned char* lds, const u16* A, int lda, const u16* Bt, int K, u16* O, int ldc, int nunits) {
;     ...
;     auto akb = [&](int kt) -> size_t { const int k0 = kt * BK; return (size_t)(REMAP ? (k0 < 768 ? k0 : (k0 < 1536 ? k0 + 384 : k0 + 1920)) : k0) * 2; };
;     ...
;         for (int t = 0; t < nt; t += 2) {
;             const bool last = (t == nt - 2);
;             const char* a1 = cA + akb(t + 1);
;             const char* a2 = last ? nA + akb(0) : cA + akb(t + 2); const char* b2 = last ? nB : cB + (size_t)(t + 2) * kstep;
;             const char* a3 = last ? nA + akb(1) : cA + akb(t + 3); const char* b3 = b2 + kstep;
;             PG8_LDB(B0, 0, 0); PG8_SCHED; PG8_LDA(At, 0, 0); PG8_STAGE(PG8_SA(1, 1), a1 + hstepA, voffA);
;             PG8_WAIT_L(8); PG8_BAR; PG8_WAIT_L(0); PG8_MMA(0, 0, At, B0); PG8_BAR; PG8_SCHED;
;             PG8_LDB(B1, 0, 1); PG8_STAGE(PG8_SB(0, 0), b2, voffB);
;             PG8_BAR; PG8_WAIT_L(0); PG8_MMA(0, 1, At, B1); PG8_BAR;
;             PG8_LDA(At, 0, 1); PG8_STAGE(PG8_SA(0, 0), a2, voffA);
;             PG8_BAR; PG8_WAIT_L(0); PG8_MMA(1, 0, At, B0); PG8_BAR; PG8_SCHED;
.LBB0_387:
	s_and_b64 s[20:21], exec, s[20:21]
	s_cselect_b32 s21, s5, s47
	s_cselect_b32 s20, s41, s46
	s_cmp_lt_u32 s50, 24
	s_cselect_b32 s51, 0x180, s68
	s_cmp_gt_u32 s50, 11
	s_cselect_b32 s51, s51, 0
	s_add_i32 s51, s51, s49
	s_lshl_b32 s51, s51, 1
	s_addk_i32 s51, 0xff00
	s_add_u32 s51, s6, s51
	s_addc_u32 s55, s7, 0
	s_add_i32 s56, 0, 0x10000
	v_add_u32_e32 v152, s56, v137
	ds_read_b128 v[140:143], v152
	ds_read_b128 v[144:147], v152 offset:1024
	ds_read_b128 v[148:151], v152 offset:2048
	ds_read_b128 v[152:155], v152 offset:3072
	s_add_u32 s54, s51, 0x1c0000
	s_addc_u32 s55, s55, 0
	v_lshl_add_u64 v[172:173], s[54:55], 0, v[134:135]
	s_add_i32 m0, s27, 0xc000
	ds_read_b128 v[156:159], v139
	ds_read_b128 v[160:163], v139 offset:1024
	ds_read_b128 v[164:167], v139 offset:2048
	ds_read_b128 v[168:171], v139 offset:3072
	ds_read_b128 v[192:195], v139 offset:4096
	ds_read_b128 v[196:199], v139 offset:5120
	ds_read_b128 v[200:203], v139 offset:6144
	ds_read_b128 v[204:207], v139 offset:7168
	global_load_lds_dwordx4 v[172:173], off
	v_lshl_add_u64 v[172:173], s[54:55], 0, v[132:133]
	s_add_i32 m0, s27, 0xe000
	s_nop 0
	global_load_lds_dwordx4 v[172:173], off
	s_waitcnt lgkmcnt(8)
	s_barrier
	s_waitcnt lgkmcnt(0)
	s_setprio 0
	s_waitcnt lgkmcnt(0)
	v_mfma_f32_16x16x32_bf16 v[126:129], v[140:143], v[156:159], v[126:129]
	v_mfma_f32_16x16x32_bf16 v[122:125], v[148:151], v[156:159], v[122:125]
	v_mfma_f32_16x16x32_bf16 v[118:121], v[140:143], v[164:167], v[118:121]
	v_mfma_f32_16x16x32_bf16 v[114:117], v[148:151], v[164:167], v[114:117]
	v_mfma_f32_16x16x32_bf16 v[102:105], v[140:143], v[192:195], v[102:105]
	v_mfma_f32_16x16x32_bf16 v[98:101], v[148:151], v[192:195], v[98:101]
	v_mfma_f32_16x16x32_bf16 v[86:89], v[140:143], v[200:203], v[86:89]
	v_mfma_f32_16x16x32_bf16 v[82:85], v[148:151], v[200:203], v[82:85]
	v_mfma_f32_16x16x32_bf16 v[126:129], v[144:147], v[160:163], v[126:129]
	v_mfma_f32_16x16x32_bf16 v[122:125], v[152:155], v[160:163], v[122:125]
	v_mfma_f32_16x16x32_bf16 v[118:121], v[144:147], v[168:171], v[118:121]
	v_mfma_f32_16x16x32_bf16 v[114:117], v[152:155], v[168:171], v[114:117]
	v_mfma_f32_16x16x32_bf16 v[102:105], v[144:147], v[196:199], v[102:105]
	v_mfma_f32_16x16x32_bf16 v[98:101], v[152:155], v[196:199], v[98:101]
	v_mfma_f32_16x16x32_bf16 v[86:89], v[144:147], v[204:207], v[86:89]
	v_mfma_f32_16x16x32_bf16 v[82:85], v[152:155], v[204:207], v[82:85]
	s_setprio 1
	s_barrier
	s_add_i32 s51, 0, 0x14000
	v_add_u32_e32 v172, s51, v137
	s_add_i32 s54, s56, s26
	ds_read_b128 v[208:211], v172
	ds_read_b128 v[212:215], v172 offset:1024
	ds_read_b128 v[216:219], v172 offset:2048
	ds_read_b128 v[220:223], v172 offset:3072
	v_lshl_add_u64 v[172:173], s[20:21], 0, v[0:1]
	s_mov_b32 m0, s54
	v_lshl_add_u64 v[224:225], s[20:21], 0, v[130:131]
	global_load_lds_dwordx4 v[172:173], off
	s_add_i32 m0, s54, 0x2000
	s_nop 0
	global_load_lds_dwordx4 v[224:225], off
	s_barrier
	s_waitcnt lgkmcnt(0)
	s_setprio 0
	s_waitcnt lgkmcnt(0)
	v_mfma_f32_16x16x32_bf16 v[110:113], v[208:211], v[156:159], v[110:113]
	v_mfma_f32_16x16x32_bf16 v[106:109], v[216:219], v[156:159], v[106:109]
	v_mfma_f32_16x16x32_bf16 v[94:97], v[208:211], v[164:167], v[94:97]
	v_mfma_f32_16x16x32_bf16 v[90:93], v[216:219], v[164:167], v[90:93]
	v_mfma_f32_16x16x32_bf16 v[78:81], v[208:211], v[192:195], v[78:81]
	v_mfma_f32_16x16x32_bf16 v[74:77], v[216:219], v[192:195], v[74:77]
	v_mfma_f32_16x16x32_bf16 v[70:73], v[208:211], v[200:203], v[70:73]
	v_mfma_f32_16x16x32_bf16 v[66:69], v[216:219], v[200:203], v[66:69]
	v_mfma_f32_16x16x32_bf16 v[110:113], v[212:215], v[160:163], v[110:113]
	v_mfma_f32_16x16x32_bf16 v[106:109], v[220:223], v[160:163], v[106:109]
	v_mfma_f32_16x16x32_bf16 v[94:97], v[212:215], v[168:171], v[94:97]
	v_mfma_f32_16x16x32_bf16 v[90:93], v[220:223], v[168:171], v[90:93]
	v_mfma_f32_16x16x32_bf16 v[78:81], v[212:215], v[196:199], v[78:81]
	v_mfma_f32_16x16x32_bf16 v[74:77], v[220:223], v[196:199], v[74:77]
	v_mfma_f32_16x16x32_bf16 v[70:73], v[212:215], v[204:207], v[70:73]
	v_mfma_f32_16x16x32_bf16 v[66:69], v[220:223], v[204:207], v[66:69]
	s_setprio 1
	s_mov_b32 m0, s27
	v_lshl_add_u64 v[226:227], s[28:29], 0, v[134:135]
	s_barrier
	ds_read_b128 v[156:159], v139 offset:16384
	ds_read_b128 v[160:163], v139 offset:17408
	ds_read_b128 v[164:167], v139 offset:18432
	ds_read_b128 v[168:171], v139 offset:19456
	ds_read_b128 v[192:195], v139 offset:20480
	ds_read_b128 v[196:199], v139 offset:21504
	ds_read_b128 v[200:203], v139 offset:22528
	ds_read_b128 v[204:207], v139 offset:23552
	global_load_lds_dwordx4 v[226:227], off
	v_lshl_add_u64 v[226:227], s[28:29], 0, v[132:133]
	s_mov_b32 m0, s30
	s_nop 0
	global_load_lds_dwordx4 v[226:227], off
	s_barrier
	s_waitcnt lgkmcnt(0)
	s_setprio 0
	s_waitcnt lgkmcnt(0)
	v_mfma_f32_16x16x32_bf16 v[62:65], v[140:143], v[156:159], v[62:65]
	v_mfma_f32_16x16x32_bf16 v[58:61], v[148:151], v[156:159], v[58:61]
	v_mfma_f32_16x16x32_bf16 v[54:57], v[140:143], v[164:167], v[54:57]
	v_mfma_f32_16x16x32_bf16 v[50:53], v[148:151], v[164:167], v[50:53]
	v_mfma_f32_16x16x32_bf16 v[38:41], v[140:143], v[192:195], v[38:41]
	v_mfma_f32_16x16x32_bf16 v[34:37], v[148:151], v[192:195], v[34:37]
	v_mfma_f32_16x16x32_bf16 v[22:25], v[140:143], v[200:203], v[22:25]
	v_mfma_f32_16x16x32_bf16 v[18:21], v[148:151], v[200:203], v[18:21]
	v_mfma_f32_16x16x32_bf16 v[62:65], v[144:147], v[160:163], v[62:65]
	v_mfma_f32_16x16x32_bf16 v[58:61], v[152:155], v[160:163], v[58:61]
	v_mfma_f32_16x16x32_bf16 v[54:57], v[144:147], v[168:171], v[54:57]
	v_mfma_f32_16x16x32_bf16 v[50:53], v[152:155], v[168:171], v[50:53]
	v_mfma_f32_16x16x32_bf16 v[38:41], v[144:147], v[196:199], v[38:41]
	v_mfma_f32_16x16x32_bf16 v[34:37], v[152:155], v[196:199], v[34:37]
	v_mfma_f32_16x16x32_bf16 v[22:25], v[144:147], v[204:207], v[22:25]
	v_mfma_f32_16x16x32_bf16 v[18:21], v[152:155], v[204:207], v[18:21]
	s_setprio 1
	s_barrier
; #define PG8_STAGE(bufoff, gbase, voff) do { _Pragma("unroll") for (int _i = 0; _i < 2; ++_i) \
;         __builtin_amdgcn_global_load_lds((const unsigned*)((const char*)(gbase) + (voff)[_i]), (LAS unsigned*)(lds + (bufoff) + ldsw + _i * 8192), 16, 0, 0); } while (0)
; #define PG8_LDA(dst, b, h) do { _Pragma("unroll") for (int m = 0; m < 4; ++m) _Pragma("unroll") for (int k = 0; k < 2; ++k) dst[m][k] = *(const LAS bf16x8*)(lds + PG8_SA(b, h) + aoff + m * 2048 + k * 1024); } while (0)
; #define PG8_LDB(dst, b, h) do { _Pragma("unroll") for (int n = 0; n < 2; ++n) _Pragma("unroll") for (int k = 0; k < 2; ++k) dst[n][k] = *(const LAS bf16x8*)(lds + PG8_SB(b, h) + boff + n * 2048 + k * 1024); } while (0)
; #define PG8_MMA(ai, bj, At, Bt_) do { __builtin_amdgcn_s_setprio(1); _Pragma("unroll") for (int m = 0; m < 4; ++m) _Pragma("unroll") for (int n = 0; n < 2; ++n) _Pragma("unroll") for (int k = 0; k < 2; ++k) \
;         acc[ai][bj][m][n] = __builtin_amdgcn_mfma_f32_16x16x32_bf16(Bt_[n][k], At[m][k], acc[ai][bj][m][n], 0, 0, 0); __builtin_amdgcn_s_setprio(0); } while (0)
; #define PG8_WAIT_V(n) asm volatile("s_waitcnt vmcnt(" #n ")" ::: "memory")
; #define PG8_WAIT_L(n) asm volatile("s_waitcnt lgkmcnt(" #n ")" ::: "memory")
; #define PG8_BAR __builtin_amdgcn_s_barrier()
; #define PG8_SCHED __builtin_amdgcn_sched_barrier(0)
; template <bool REMAP>
; DI void gemm_phase(LAS unsigned char* lds, const u16* A, int lda, const u16* Bt, int K, u16* O, int ldc, int nunits) {
;     ...
;             PG8_STAGE(PG8_SB(0, 1), b2 + hstepB, voffB);
;             PG8_WAIT_V(6); PG8_BAR; PG8_MMA(1, 1, At, B1); PG8_BAR;
;             PG8_LDB(B0, 1, 0); PG8_SCHED; PG8_LDA(At, 1, 0); PG8_STAGE(PG8_SA(0, 1), a2 + hstepA, voffA);
;             PG8_WAIT_L(8); PG8_BAR; PG8_WAIT_L(0); PG8_MMA(0, 0, At, B0); PG8_BAR; PG8_SCHED;
;             PG8_LDB(B1, 1, 1); PG8_STAGE(PG8_SB(1, 0), b3, voffB);
	s_add_u32 s54, s20, 0x80000
	s_addc_u32 s55, s21, 0
	s_add_i32 s51, s51, s26
	v_lshl_add_u64 v[140:141], s[54:55], 0, v[0:1]
	s_mov_b32 m0, s51
	s_nop 0
	global_load_lds_dwordx4 v[140:141], off
	v_lshl_add_u64 v[140:141], s[54:55], 0, v[130:131]
	s_add_i32 m0, s51, 0x2000
	s_nop 0
	global_load_lds_dwordx4 v[140:141], off
	s_waitcnt vmcnt(6)
	s_barrier
	s_setprio 0
	v_mfma_f32_16x16x32_bf16 v[46:49], v[208:211], v[156:159], v[46:49]
	v_mfma_f32_16x16x32_bf16 v[42:45], v[216:219], v[156:159], v[42:45]
	v_mfma_f32_16x16x32_bf16 v[30:33], v[208:211], v[164:167], v[30:33]
	v_mfma_f32_16x16x32_bf16 v[26:29], v[216:219], v[164:167], v[26:29]
	v_mfma_f32_16x16x32_bf16 v[14:17], v[208:211], v[192:195], v[14:17]
	v_mfma_f32_16x16x32_bf16 v[10:13], v[216:219], v[192:195], v[10:13]
	v_mfma_f32_16x16x32_bf16 v[6:9], v[208:211], v[200:203], v[6:9]
	v_mfma_f32_16x16x32_bf16 v[2:5], v[216:219], v[200:203], v[2:5]
	v_mfma_f32_16x16x32_bf16 v[46:49], v[212:215], v[160:163], v[46:49]
	v_mfma_f32_16x16x32_bf16 v[42:45], v[220:223], v[160:163], v[42:45]
	v_mfma_f32_16x16x32_bf16 v[30:33], v[212:215], v[168:171], v[30:33]
	v_mfma_f32_16x16x32_bf16 v[26:29], v[220:223], v[168:171], v[26:29]
	v_mfma_f32_16x16x32_bf16 v[14:17], v[212:215], v[196:199], v[14:17]
	v_mfma_f32_16x16x32_bf16 v[10:13], v[220:223], v[196:199], v[10:13]
	v_mfma_f32_16x16x32_bf16 v[6:9], v[212:215], v[204:207], v[6:9]
	v_mfma_f32_16x16x32_bf16 v[2:5], v[220:223], v[204:207], v[2:5]
	s_setprio 1
	s_add_i32 s51, 0, 0x18000
	v_add_u32_e32 v152, s51, v137
	s_barrier
	ds_read_b128 v[140:143], v152
	ds_read_b128 v[144:147], v152 offset:1024
	ds_read_b128 v[148:151], v152 offset:2048
	ds_read_b128 v[152:155], v152 offset:3072
	s_add_u32 s28, s28, 0x1c0000
	s_addc_u32 s29, s29, 0
	s_mov_b32 m0, s31
	v_lshl_add_u64 v[208:209], s[28:29], 0, v[134:135]
	ds_read_b128 v[156:159], v139 offset:32768
	ds_read_b128 v[160:163], v139 offset:33792
	ds_read_b128 v[164:167], v139 offset:34816
	ds_read_b128 v[168:171], v139 offset:35840
	ds_read_b128 v[192:195], v139 offset:36864
	ds_read_b128 v[196:199], v139 offset:37888
	ds_read_b128 v[200:203], v139 offset:38912
	ds_read_b128 v[204:207], v139 offset:39936
	global_load_lds_dwordx4 v[208:209], off
	v_lshl_add_u64 v[208:209], s[28:29], 0, v[132:133]
	s_mov_b32 m0, s34
	s_nop 0
	global_load_lds_dwordx4 v[208:209], off
	s_waitcnt lgkmcnt(8)
	s_barrier
	s_waitcnt lgkmcnt(0)
	s_setprio 0
	s_waitcnt lgkmcnt(0)
	v_mfma_f32_16x16x32_bf16 v[126:129], v[140:143], v[156:159], v[126:129]
	v_mfma_f32_16x16x32_bf16 v[122:125], v[148:151], v[156:159], v[122:125]
	v_mfma_f32_16x16x32_bf16 v[118:121], v[140:143], v[164:167], v[118:121]
	v_mfma_f32_16x16x32_bf16 v[114:117], v[148:151], v[164:167], v[114:117]
	v_mfma_f32_16x16x32_bf16 v[102:105], v[140:143], v[192:195], v[102:105]
	v_mfma_f32_16x16x32_bf16 v[98:101], v[148:151], v[192:195], v[98:101]
	v_mfma_f32_16x16x32_bf16 v[86:89], v[140:143], v[200:203], v[86:89]
	v_mfma_f32_16x16x32_bf16 v[82:85], v[148:151], v[200:203], v[82:85]
	v_mfma_f32_16x16x32_bf16 v[126:129], v[144:147], v[160:163], v[126:129]
	v_mfma_f32_16x16x32_bf16 v[122:125], v[152:155], v[160:163], v[122:125]
	v_mfma_f32_16x16x32_bf16 v[118:121], v[144:147], v[168:171], v[118:121]
	v_mfma_f32_16x16x32_bf16 v[114:117], v[152:155], v[168:171], v[114:117]
	v_mfma_f32_16x16x32_bf16 v[102:105], v[144:147], v[196:199], v[102:105]
	v_mfma_f32_16x16x32_bf16 v[98:101], v[152:155], v[196:199], v[98:101]
	v_mfma_f32_16x16x32_bf16 v[86:89], v[144:147], v[204:207], v[86:89]
	v_mfma_f32_16x16x32_bf16 v[82:85], v[152:155], v[204:207], v[82:85]
	s_setprio 1
	s_barrier
	s_add_i32 s28, 0, 0x1c000
	s_add_i32 s29, s51, s26
	v_add_u32_e32 v220, s28, v137
	v_lshl_add_u64 v[172:173], v[172:173], 0, s[18:19]
	s_mov_b32 m0, s29
	ds_read_b128 v[208:211], v220
	ds_read_b128 v[212:215], v220 offset:1024
	ds_read_b128 v[216:219], v220 offset:2048
	ds_read_b128 v[220:223], v220 offset:3072
	global_load_lds_dwordx4 v[172:173], off
	v_lshl_add_u64 v[172:173], v[224:225], 0, s[18:19]
	s_add_i32 m0, s29, 0x2000
	s_nop 0
	global_load_lds_dwordx4 v[172:173], off
	s_barrier
; #define PG8_STAGE(bufoff, gbase, voff) do { _Pragma("unroll") for (int _i = 0; _i < 2; ++_i) \
;         __builtin_amdgcn_global_load_lds((const unsigned*)((const char*)(gbase) + (voff)[_i]), (LAS unsigned*)(lds + (bufoff) + ldsw + _i * 8192), 16, 0, 0); } while (0)
; #define PG8_LDA(dst, b, h) do { _Pragma("unroll") for (int m = 0; m < 4; ++m) _Pragma("unroll") for (int k = 0; k < 2; ++k) dst[m][k] = *(const LAS bf16x8*)(lds + PG8_SA(b, h) + aoff + m * 2048 + k * 1024); } while (0)
; #define PG8_MMA(ai, bj, At, Bt_) do { __builtin_amdgcn_s_setprio(1); _Pragma("unroll") for (int m = 0; m < 4; ++m) _Pragma("unroll") for (int n = 0; n < 2; ++n) _Pragma("unroll") for (int k = 0; k < 2; ++k) \
;         acc[ai][bj][m][n] = __builtin_amdgcn_mfma_f32_16x16x32_bf16(Bt_[n][k], At[m][k], acc[ai][bj][m][n], 0, 0, 0); __builtin_amdgcn_s_setprio(0); } while (0)
; #define PG8_WAIT_V(n) asm volatile("s_waitcnt vmcnt(" #n ")" ::: "memory")
; #define PG8_WAIT_L(n) asm volatile("s_waitcnt lgkmcnt(" #n ")" ::: "memory")
; #define PG8_BAR __builtin_amdgcn_s_barrier()
; #define PG8_SCHED __builtin_amdgcn_sched_barrier(0)
; template <bool REMAP>
; DI void gemm_phase(LAS unsigned char* lds, const u16* A, int lda, const u16* Bt, int K, u16* O, int ldc, int nunits) {
;     ...
;             PG8_BAR; PG8_WAIT_L(0); PG8_MMA(0, 1, At, B1); PG8_BAR;
;             PG8_LDA(At, 1, 1); PG8_STAGE(PG8_SA(1, 0), a3, voffA);
;             PG8_BAR; PG8_WAIT_L(0); PG8_MMA(1, 0, At, B0); PG8_BAR; PG8_SCHED;
;             PG8_STAGE(PG8_SB(1, 1), b3 + hstepB, voffB);
;             PG8_WAIT_V(6); PG8_BAR; PG8_MMA(1, 1, At, B1); PG8_BAR;
	s_waitcnt lgkmcnt(0)
	s_setprio 0
	s_waitcnt lgkmcnt(0)
	v_mfma_f32_16x16x32_bf16 v[110:113], v[208:211], v[156:159], v[110:113]
	v_mfma_f32_16x16x32_bf16 v[106:109], v[216:219], v[156:159], v[106:109]
	v_mfma_f32_16x16x32_bf16 v[94:97], v[208:211], v[164:167], v[94:97]
	v_mfma_f32_16x16x32_bf16 v[90:93], v[216:219], v[164:167], v[90:93]
	v_mfma_f32_16x16x32_bf16 v[78:81], v[208:211], v[192:195], v[78:81]
	v_mfma_f32_16x16x32_bf16 v[74:77], v[216:219], v[192:195], v[74:77]
	v_mfma_f32_16x16x32_bf16 v[70:73], v[208:211], v[200:203], v[70:73]
	v_mfma_f32_16x16x32_bf16 v[66:69], v[216:219], v[200:203], v[66:69]
	v_mfma_f32_16x16x32_bf16 v[110:113], v[212:215], v[160:163], v[110:113]
	v_mfma_f32_16x16x32_bf16 v[106:109], v[220:223], v[160:163], v[106:109]
	v_mfma_f32_16x16x32_bf16 v[94:97], v[212:215], v[168:171], v[94:97]
	v_mfma_f32_16x16x32_bf16 v[90:93], v[220:223], v[168:171], v[90:93]
	v_mfma_f32_16x16x32_bf16 v[78:81], v[212:215], v[196:199], v[78:81]
	v_mfma_f32_16x16x32_bf16 v[74:77], v[220:223], v[196:199], v[74:77]
	v_mfma_f32_16x16x32_bf16 v[70:73], v[212:215], v[204:207], v[70:73]
	v_mfma_f32_16x16x32_bf16 v[66:69], v[220:223], v[204:207], v[66:69]
	s_setprio 1
	s_mov_b32 m0, s35
	v_lshl_add_u64 v[172:173], s[22:23], 0, v[134:135]
	s_barrier
	ds_read_b128 v[156:159], v139 offset:49152
	ds_read_b128 v[160:163], v139 offset:50176
	ds_read_b128 v[164:167], v139 offset:51200
	ds_read_b128 v[168:171], v139 offset:52224
	ds_read_b128 v[192:195], v139 offset:53248
	ds_read_b128 v[196:199], v139 offset:54272
	ds_read_b128 v[200:203], v139 offset:55296
	ds_read_b128 v[204:207], v139 offset:56320
	global_load_lds_dwordx4 v[172:173], off
	v_lshl_add_u64 v[172:173], s[22:23], 0, v[132:133]
	s_mov_b32 m0, s36
	s_nop 0
	global_load_lds_dwordx4 v[172:173], off
	s_barrier
	s_waitcnt lgkmcnt(0)
	s_setprio 0
	s_waitcnt lgkmcnt(0)
	v_mfma_f32_16x16x32_bf16 v[62:65], v[140:143], v[156:159], v[62:65]
	v_mfma_f32_16x16x32_bf16 v[58:61], v[148:151], v[156:159], v[58:61]
	v_mfma_f32_16x16x32_bf16 v[54:57], v[140:143], v[164:167], v[54:57]
	v_mfma_f32_16x16x32_bf16 v[50:53], v[148:151], v[164:167], v[50:53]
	v_mfma_f32_16x16x32_bf16 v[38:41], v[140:143], v[192:195], v[38:41]
	v_mfma_f32_16x16x32_bf16 v[34:37], v[148:151], v[192:195], v[34:37]
	v_mfma_f32_16x16x32_bf16 v[22:25], v[140:143], v[200:203], v[22:25]
	v_mfma_f32_16x16x32_bf16 v[18:21], v[148:151], v[200:203], v[18:21]
	v_mfma_f32_16x16x32_bf16 v[62:65], v[144:147], v[160:163], v[62:65]
	v_mfma_f32_16x16x32_bf16 v[58:61], v[152:155], v[160:163], v[58:61]
	v_mfma_f32_16x16x32_bf16 v[54:57], v[144:147], v[168:171], v[54:57]
	v_mfma_f32_16x16x32_bf16 v[50:53], v[152:155], v[168:171], v[50:53]
	v_mfma_f32_16x16x32_bf16 v[38:41], v[144:147], v[196:199], v[38:41]
	v_mfma_f32_16x16x32_bf16 v[34:37], v[152:155], v[196:199], v[34:37]
	v_mfma_f32_16x16x32_bf16 v[22:25], v[144:147], v[204:207], v[22:25]
	v_mfma_f32_16x16x32_bf16 v[18:21], v[152:155], v[204:207], v[18:21]
	s_setprio 1
	s_barrier
	s_add_u32 s20, s20, 0x80080
	s_addc_u32 s21, s21, 0
	s_add_i32 s22, s28, s26
	v_lshl_add_u64 v[140:141], s[20:21], 0, v[0:1]
	s_mov_b32 m0, s22
	s_nop 0
	global_load_lds_dwordx4 v[140:141], off
	v_lshl_add_u64 v[140:141], s[20:21], 0, v[130:131]
	s_add_i32 m0, s22, 0x2000
	s_nop 0
	global_load_lds_dwordx4 v[140:141], off
	s_waitcnt vmcnt(6)
	s_barrier
	s_setprio 0
	v_mfma_f32_16x16x32_bf16 v[46:49], v[208:211], v[156:159], v[46:49]
	v_mfma_f32_16x16x32_bf16 v[42:45], v[216:219], v[156:159], v[42:45]
	v_mfma_f32_16x16x32_bf16 v[30:33], v[208:211], v[164:167], v[30:33]
	v_mfma_f32_16x16x32_bf16 v[26:29], v[216:219], v[164:167], v[26:29]
	v_mfma_f32_16x16x32_bf16 v[14:17], v[208:211], v[192:195], v[14:17]
	v_mfma_f32_16x16x32_bf16 v[10:13], v[216:219], v[192:195], v[10:13]
	v_mfma_f32_16x16x32_bf16 v[6:9], v[208:211], v[200:203], v[6:9]
	v_mfma_f32_16x16x32_bf16 v[2:5], v[216:219], v[200:203], v[2:5]
	v_mfma_f32_16x16x32_bf16 v[46:49], v[212:215], v[160:163], v[46:49]
	v_mfma_f32_16x16x32_bf16 v[42:45], v[220:223], v[160:163], v[42:45]
	v_mfma_f32_16x16x32_bf16 v[30:33], v[212:215], v[168:171], v[30:33]
	v_mfma_f32_16x16x32_bf16 v[26:29], v[220:223], v[168:171], v[26:29]
	v_mfma_f32_16x16x32_bf16 v[14:17], v[212:215], v[196:199], v[14:17]
	v_mfma_f32_16x16x32_bf16 v[10:13], v[220:223], v[196:199], v[10:13]
	v_mfma_f32_16x16x32_bf16 v[6:9], v[212:215], v[204:207], v[6:9]
	v_mfma_f32_16x16x32_bf16 v[2:5], v[220:223], v[204:207], v[2:5]
	s_setprio 1
	s_add_i32 s20, s50, 2
	s_add_u32 s46, s46, 0x100
	s_addc_u32 s47, s47, 0
	s_addk_i32 s49, 0x80
	s_cmp_gt_u32 s50, 29
	s_mov_b32 s50, s20
	s_barrier
	s_cbranch_scc1 .LBB0_381
